# attention: more hazard-free nops removed; pass prologue waits only for the K/V tiles it needs (vmcnt(2/3) instead of vmcnt(0))
# baseline (speedup 1.0000x reference)
; __device__ __forceinline__ int make_tid(int wave0) { int t = wave0 * 64 + (int)__builtin_amdgcn_mbcnt_hi(~0u, __builtin_amdgcn_mbcnt_lo(~0u, 0u)); asm volatile("" : "+v"(t)); return t; }
; #define AT_WAITBAR(N) asm volatile("s_waitcnt vmcnt(" #N ") lgkmcnt(0)\n\ts_barrier" ::: "memory")
; template <int DQK, int MODE> ...
;     ...
;     const int tid = make_tid(wave0), lane = tid & 63, r32 = lane & 31, hi = lane >> 5;
;     const int wid = wave0;
;     const int tw0 = t0 + 32 * wid, tq = tw0 + r32;
;     bf16x8 qf[NDS];
; #pragma unroll
;     for (int ds = 0; ds < NDS; ++ds) qf[ds] = *(const bf16x8*)(Qp + (size_t)tq * qs + 16 * ds + 8 * hi);
;     int kt_lo = 0; const int kt_hi = (t0 >> 6) + 3;
;     if (MODE == 1) { const int lo = t0 - 511; kt_lo = lo > 0 ? (lo >> 6) : 0; }
;     unsigned long long selm = 0ull; if (MODE == 2) selm = selp[tq];
;     const int kc0 = wid % CPR, kc1 = (8 + (wid & 3)) % CPR;
;     const bf16_t* ksrc0 = Kp + (size_t)lane * ks + kc0 * 8;
;     const bf16_t* ksrc1 = Kp + (size_t)lane * ks + kc1 * 8;
;     const bf16_t* vsrc = Vp + (size_t)(16 * (wid & 3) + (lane >> 2)) * vs + (wid >> 2) * 32 + (lane & 3) * 8;
;     ...
;     o[0] = f32x16{}; o[1] = f32x16{};
;     float m_run = 0.f, l_run = 0.f; bool init = false;
;     f32x16 negm = f32x16{}; asm volatile("" : "+v"(negm));
;     f32x16 pa0 = f32x16{}, pa1 = f32x16{}, pb0 = f32x16{}, pb1 = f32x16{};
;     bf16x8 kf[2 * NDS];
;     AT_DMAK(kt_lo); AT_DMAV(kt_lo); AT_DMAK(kt_lo + 1); AT_DMAK(kt_lo + 2); AT_DMAV(kt_lo + 1);
;     if (NKW > 1) AT_WAITBAR(3); else AT_WAITBAR(2);
;     { AT_KFRAG(kt_lo); asm volatile("s_waitcnt lgkmcnt(0)\n\ts_barrier" ::: "memory");
;       const float b_ = AT_BIAS(kt_lo); AT_QKM(pa0, pa1, AT_SPLAT(b_)); }
;     const int vfo = ((lane >> 4) & 1) * 32 + (lane & 3) * 8 + (4 * hi + ((lane & 15) >> 2)) * 64;
; __device__ __forceinline__ void attn_phase(LAS unsigned char* lds, int* counter, const bf16_t* __restrict__ P, const bf16_t* __restrict__ Qm, const bf16_t* __restrict__ Kmla, ...
;     ...
;             const int b = (r - 64) >> 3, head = (r - 64) & 7, g = head >> 2;
;             const bf16_t* Pb = P + (size_t)b * SEQ * NPJ;
;             attn_pass<64, 2>(lds, Pb + C_NQ + head * 64, NPJ, Pb + C_NKV + 256 + g * 64, NPJ, Pb + C_NKV + 384 + g * 64, NPJ, t0, mask + (size_t)(b * 2 + g) * SEQ, o, linv, wave0);
.LBB0_683:
	s_not_b32 s2, s5
	s_lshl_b32 s2, s2, 8
	s_and_b32 s40, s2, 0xf00
	s_add_i32 s39, s40, s55
	v_bfe_u32 v190, v191, 5, 1
	v_and_or_b32 v214, v191, 31, s39
	s_cmp_gt_i32 s41, 31
	s_mov_b64 s[2:3], -1
	s_cbranch_scc0 .LBB0_728
	s_cmp_gt_u32 s41, 63
	s_cbranch_scc0 .LBB0_713
	s_sub_i32 s2, s41, 64
	s_lshr_b32 s22, s2, 3
	s_and_b32 s47, s41, 7
	s_bfe_u32 s4, s41, 0x10002
	s_mul_i32 s3, s22, 0x1400000
	v_readlane_b32 s6, v254, 48
	s_mul_hi_u32 s2, s22, 0x1400000
	v_readlane_b32 s7, v254, 49
	s_add_u32 s45, s6, s3
	s_addc_u32 s44, s7, s2
	s_lshl_b32 s42, s47, 6
	s_lshl_b32 s2, s47, 7
	s_add_u32 s16, s45, s2
	s_addc_u32 s17, s44, 0
	s_lshl_b32 s46, s4, 6
	s_lshl_b32 s2, s4, 7
	s_add_u32 s2, s45, s2
	s_addc_u32 s3, s44, 0
	s_lshl_b32 s5, s22, 1
	s_or_b32 s80, s5, s4
	s_lshl_b64 s[4:5], s[80:81], 15
	v_mov_b32_e32 v20, v246
	s_add_u32 s4, s34, s4
	s_addc_u32 s5, s35, s5
	v_and_b32_e32 v21, 31, v20
	v_or_b32_e32 v0, s39, v21
	v_mov_b32_e32 v1, v215
	v_lshl_add_u64 v[2:3], v[0:1], 3, s[4:5]
	global_load_dwordx2 v[144:145], v[2:3], off
	v_bfe_u32 v22, v20, 5, 1
	v_mov_b64_e32 v[2:3], s[16:17]
	v_mad_u64_u32 v[0:1], s[4:5], v0, s65, v[2:3]
	v_lshlrev_b32_e32 v2, 4, v22
	v_mov_b32_e32 v3, v215
	v_lshl_add_u64 v[0:1], v[0:1], 0, v[2:3]
	global_load_dwordx4 v[96:99], v[0:1], off offset:2368
	global_load_dwordx4 v[100:103], v[0:1], off offset:2400
	global_load_dwordx4 v[104:107], v[0:1], off offset:2432
	global_load_dwordx4 v[108:111], v[0:1], off offset:2464
	v_and_b32_e32 v4, 63, v20
	v_mul_u32_u24_e32 v0, 0xa00, v4
	v_lshlrev_b32_e32 v0, 1, v0
	v_mov_b32_e32 v1, v215
	v_lshl_add_u64 v[0:1], s[2:3], 0, v[0:1]
	s_lshl_b32 s18, s58, 1
	s_mov_b32 s19, s81
	v_lshl_add_u64 v[146:147], v[0:1], 0, s[18:19]
	v_bfe_u32 v0, v20, 2, 4
	v_or_b32_e32 v0, s59, v0
	v_mul_u32_u24_e32 v0, 0xa00, v0
	v_lshlrev_b32_e32 v0, 1, v0
	v_mov_b32_e32 v1, v215
	v_lshlrev_b32_e32 v2, 3, v20
	v_lshl_add_u64 v[0:1], s[2:3], 0, v[0:1]
	s_lshl_b32 s20, s60, 1
	s_mov_b32 s21, s81
	v_and_b32_e32 v23, 24, v2
	s_mov_b64 s[4:5], 0xf40
	v_lshl_add_u64 v[0:1], v[0:1], 0, s[20:21]
	v_lshlrev_b32_e32 v2, 1, v23
	s_mov_b32 m0, s61
	v_lshl_add_u64 v[16:17], v[146:147], 0, s[4:5]
	v_lshl_add_u64 v[18:19], v[0:1], 0, v[2:3]
	s_mov_b64 s[2:3], 0x1040
	v_mov_b32_e32 v0, v215
	v_mov_b32_e32 v1, v215
	v_mov_b32_e32 v2, v215
	v_mov_b32_e32 v4, v215
	v_mov_b32_e32 v5, v215
	v_mov_b32_e32 v6, v215
	v_mov_b32_e32 v7, v215
	v_mov_b32_e32 v8, v215
	v_mov_b32_e32 v9, v215
	v_mov_b32_e32 v10, v215
	v_mov_b32_e32 v11, v215
	v_mov_b32_e32 v12, v215
	v_mov_b32_e32 v13, v215
	v_mov_b32_e32 v14, v215
	v_mov_b32_e32 v15, v215
	v_lshl_add_u64 v[148:149], v[18:19], 0, s[2:3]
	global_load_lds_dwordx4 v[16:17], off
	s_mov_b32 m0, s82
	s_mov_b64 s[2:3], 0x50f40
	global_load_lds_dwordx4 v[148:149], off
	v_lshl_add_u64 v[0:1], v[146:147], 0, s[2:3]
	s_mov_b32 m0, s69
	s_mov_b64 s[2:3], 0xa0f40
	global_load_lds_dwordx4 v[0:1], off
	v_lshl_add_u64 v[0:1], v[146:147], 0, s[2:3]
	s_mov_b32 m0, s68
	s_mov_b64 s[2:3], 0x51040
	global_load_lds_dwordx4 v[0:1], off
	v_lshl_add_u64 v[0:1], v[18:19], 0, s[2:3]
	s_mov_b32 m0, s83
	v_lshlrev_b32_e32 v151, 10, v22
	global_load_lds_dwordx4 v[0:1], off
	v_lshlrev_b32_e32 v152, 4, v21
	s_waitcnt vmcnt(2) lgkmcnt(0)
	s_barrier
	v_add3_u32 v153, 0, v151, v152
	ds_read_b128 v[0:3], v153
	ds_read_b128 v[4:7], v153 offset:512
	v_mov_b32_e32 v9, v215
	s_lshr_b32 s2, s40, 6
	v_mov_b32_e32 v154, 0
	s_mov_b32 s23, s81
	s_waitcnt vmcnt(2)
	v_and_b32_e32 v8, 1, v144
	v_cmp_eq_u64_e32 vcc, 0, v[8:9]
	s_mov_b32 s19, 1
	s_mov_b32 s21, 4
	v_cndmask_b32_e32 v32, 0, v249, vcc
	v_mov_b32_e32 v33, v32
	v_mov_b32_e32 v34, v32
	v_mov_b32_e32 v35, v32
	v_mov_b32_e32 v36, v32
	v_mov_b32_e32 v37, v32
	v_mov_b32_e32 v38, v32
	v_mov_b32_e32 v39, v32
	v_mov_b32_e32 v40, v32
	v_mov_b32_e32 v41, v32
	v_mov_b32_e32 v42, v32
	v_mov_b32_e32 v43, v32
	v_mov_b32_e32 v44, v32
	v_mov_b32_e32 v45, v32
	v_mov_b32_e32 v46, v32
	v_mov_b32_e32 v47, v32
	s_mov_b32 s48, 0
	s_or_b32 s43, s2, 3
	s_waitcnt lgkmcnt(0)
	v_mfma_f32_32x32x16_bf16 v[48:63], v[0:3], v[96:99], v[32:47]
	s_mov_b64 s[2:3], 0
	s_movk_i32 s49, 0x7f
	v_mov_b32_e32 v150, 0
	v_mov_b32_e32 v8, v154
	v_mov_b32_e32 v9, v154
	v_mov_b32_e32 v10, v154
	v_mov_b32_e32 v11, v154
	v_mfma_f32_32x32x16_bf16 v[32:47], v[4:7], v[96:99], v[32:47]
	ds_read_b128 v[0:3], v153 offset:2048
	ds_read_b128 v[4:7], v153 offset:2560
	v_mov_b32_e32 v12, v154
	v_mov_b32_e32 v13, v154
	v_mov_b32_e32 v14, v154
	v_mov_b32_e32 v15, v154
	v_mov_b32_e32 v16, v154
	v_mov_b32_e32 v17, v154
	s_waitcnt lgkmcnt(1)
	v_mfma_f32_32x32x16_bf16 v[48:63], v[0:3], v[100:103], v[48:63]
	v_mov_b32_e32 v18, v154
	v_mov_b32_e32 v19, v154
	v_mov_b32_e32 v24, v154
	v_mov_b32_e32 v25, v154
	v_mov_b32_e32 v26, v154
	v_mov_b32_e32 v27, v154
	v_mov_b32_e32 v28, v154
	s_waitcnt lgkmcnt(0)
	v_mfma_f32_32x32x16_bf16 v[32:47], v[4:7], v[100:103], v[32:47]
	ds_read_b128 v[0:3], v153 offset:4096
	ds_read_b128 v[4:7], v153 offset:4608
	v_mov_b32_e32 v29, v154
	v_mov_b32_e32 v30, v154
	v_mov_b32_e32 v31, v154
	s_waitcnt lgkmcnt(1)
	v_mfma_f32_32x32x16_bf16 v[48:63], v[0:3], v[104:107], v[48:63]
	s_waitcnt lgkmcnt(0)
	v_mfma_f32_32x32x16_bf16 v[32:47], v[4:7], v[104:107], v[32:47]
	ds_read_b128 v[0:3], v153 offset:6144
	ds_read_b128 v[4:7], v153 offset:6656
	s_waitcnt lgkmcnt(0)
	s_barrier
	s_waitcnt lgkmcnt(1)
	v_mfma_f32_32x32x16_bf16 v[48:63], v[0:3], v[108:111], v[48:63]
	v_lshlrev_b32_e32 v2, 4, v20
	v_lshlrev_b32_e32 v0, 1, v20
	v_and_b32_e32 v2, 0xc0, v2
	v_and_b32_e32 v0, 32, v0
	v_lshl_or_b32 v2, v22, 8, v2
	v_or3_b32 v0, v2, v0, v23
	v_lshlrev_b32_e32 v1, 2, v22
	s_waitcnt lgkmcnt(0)
	v_mfma_f32_32x32x16_bf16 v[32:47], v[4:7], v[108:111], v[32:47]
	v_add_u32_e32 v155, 0, v0
	v_add_u32_e32 v0, s39, v21
	v_sub_u32_e32 v156, v0, v1
	v_mov_b32_e32 v0, 0
	v_mov_b32_e32 v1, v154
	v_mov_b32_e32 v2, v154
	v_mov_b32_e32 v3, v154
	v_mov_b32_e32 v4, v154
	v_mov_b32_e32 v5, v154
	v_mov_b32_e32 v6, v154
	v_mov_b32_e32 v7, v154
	v_mov_b32_e32 v20, v154
	v_mov_b32_e32 v21, v154
	v_mov_b32_e32 v22, v154
	v_mov_b32_e32 v23, v154
	s_branch .LBB0_689

.LBB0_687:
	s_mul_hi_u32 s4, s19, 0xaaaaaaab
	s_lshr_b32 s4, s4, 1
	s_mul_i32 s4, s4, 0xffff4000
	v_lshrrev_b64 v[34:35], s51, v[144:145]
	v_and_b32_e32 v33, 1, v34
	v_cmp_eq_u32_e32 vcc, 1, v33
	v_exp_f32_e32 v80, v80
	v_exp_f32_e32 v81, v81
	v_cndmask_b32_e32 v32, v249, v32, vcc
	v_mov_b32_e32 v33, v32
	v_mov_b32_e32 v34, v32
	v_mov_b32_e32 v35, v32
	v_mov_b32_e32 v36, v32
	v_mov_b32_e32 v37, v32
	v_mov_b32_e32 v38, v32
	v_mov_b32_e32 v39, v32
	v_mov_b32_e32 v40, v32
	v_mov_b32_e32 v41, v32
	v_mov_b32_e32 v42, v32
	v_mov_b32_e32 v43, v32
	v_mov_b32_e32 v44, v32
	v_mov_b32_e32 v45, v32
	v_mov_b32_e32 v46, v32
	v_mov_b32_e32 v47, v32
	v_exp_f32_e32 v82, v82
	v_exp_f32_e32 v83, v83
	s_waitcnt lgkmcnt(0)
	v_mfma_f32_32x32x16_bf16 v[48:63], v[140:143], v[96:99], v[32:47]
	v_add_u32_e32 v140, s4, v155
	v_exp_f32_e32 v84, v84
	v_exp_f32_e32 v85, v85
	v_exp_f32_e32 v86, v86
	v_exp_f32_e32 v87, v87
	v_exp_f32_e32 v88, v88
	v_exp_f32_e32 v89, v89
	v_mfma_f32_32x32x16_bf16 v[32:47], v[132:135], v[96:99], v[32:47]
	v_exp_f32_e32 v90, v90
	v_exp_f32_e32 v91, v91
	v_exp_f32_e32 v92, v92
	v_exp_f32_e32 v93, v93
	v_exp_f32_e32 v94, v94
	v_exp_f32_e32 v95, v95
	v_mfma_f32_32x32x16_bf16 v[48:63], v[136:139], v[100:103], v[48:63]
	ds_read_b64_tr_b16 v[132:133], v140 offset:24576
	ds_read_b64_tr_b16 v[134:135], v140 offset:25088
	ds_read_b64_tr_b16 v[136:137], v140 offset:25600
	ds_read_b64_tr_b16 v[138:139], v140 offset:26112
	v_mfma_f32_32x32x16_bf16 v[48:63], v[128:131], v[104:107], v[48:63]
	v_mfma_f32_32x32x16_bf16 v[32:47], v[120:123], v[100:103], v[32:47]
	v_mfma_f32_32x32x16_bf16 v[48:63], v[124:127], v[108:111], v[48:63]
	ds_read_b64_tr_b16 v[120:121], v140 offset:28672
	ds_read_b64_tr_b16 v[122:123], v140 offset:29184
	ds_read_b64_tr_b16 v[124:125], v140 offset:29696
	ds_read_b64_tr_b16 v[126:127], v140 offset:30208
	v_add_f32_e32 v128, v215, v80
	v_add_f32_e32 v129, v215, v81
	v_cvt_pk_bf16_f32 v80, v80, v81
	v_add_f32_e32 v128, v128, v82
	v_mfma_f32_32x32x16_bf16 v[32:47], v[116:119], v[104:107], v[32:47]
	v_add_f32_e32 v116, v129, v83
	v_add_f32_e32 v117, v128, v84
	v_cvt_pk_bf16_f32 v81, v82, v83
	v_add_f32_e32 v116, v116, v85
	v_add_f32_e32 v117, v117, v86
	v_cvt_pk_bf16_f32 v82, v84, v85
	v_add_f32_e32 v116, v116, v87
	v_add_f32_e32 v117, v117, v88
	v_cvt_pk_bf16_f32 v83, v86, v87
	v_add_f32_e32 v116, v116, v89
	v_add_f32_e32 v117, v117, v90
	v_cvt_pk_bf16_f32 v84, v88, v89
	v_add_f32_e32 v116, v116, v91
	v_add_f32_e32 v117, v117, v92
	v_cvt_pk_bf16_f32 v85, v90, v91
	v_add_f32_e32 v116, v116, v93
	v_add_f32_e32 v117, v117, v94
	v_cvt_pk_bf16_f32 v86, v92, v93
	v_add_f32_e32 v116, v116, v95
	v_cvt_pk_bf16_f32 v87, v94, v95
	s_waitcnt lgkmcnt(0)
	v_mfma_f32_32x32x16_bf16 v[0:15], v[132:135], v[80:83], v[0:15]
	v_exp_f32_e32 v64, v64
	v_exp_f32_e32 v65, v65
	v_exp_f32_e32 v66, v66
	v_exp_f32_e32 v67, v67
	v_exp_f32_e32 v68, v68
	v_exp_f32_e32 v69, v69
	v_exp_f32_e32 v70, v70
	v_mfma_f32_32x32x16_bf16 v[16:31], v[120:123], v[80:83], v[16:31]
	v_exp_f32_e32 v71, v71
	v_exp_f32_e32 v72, v72
	v_exp_f32_e32 v73, v73
	v_exp_f32_e32 v74, v74
	v_exp_f32_e32 v75, v75
	v_exp_f32_e32 v76, v76
	v_exp_f32_e32 v77, v77
	v_mfma_f32_32x32x16_bf16 v[0:15], v[136:139], v[84:87], v[0:15]
	v_exp_f32_e32 v78, v78
	v_exp_f32_e32 v79, v79
	v_mfma_f32_32x32x16_bf16 v[16:31], v[124:127], v[84:87], v[16:31]
	ds_read_b64_tr_b16 v[80:81], v140 offset:26624
	ds_read_b64_tr_b16 v[82:83], v140 offset:27136
	ds_read_b64_tr_b16 v[84:85], v140 offset:30720
	ds_read_b64_tr_b16 v[86:87], v140 offset:31232
	ds_read_b64_tr_b16 v[88:89], v140 offset:27648
	ds_read_b64_tr_b16 v[90:91], v140 offset:28160
	ds_read_b64_tr_b16 v[92:93], v140 offset:31744
	ds_read_b64_tr_b16 v[94:95], v140 offset:32256
	v_add_f32_e32 v117, v117, v64
	v_add_f32_e32 v116, v116, v65
	v_cvt_pk_bf16_f32 v64, v64, v65
	v_add_f32_e32 v117, v117, v66
	v_add_f32_e32 v116, v116, v67
	v_cvt_pk_bf16_f32 v65, v66, v67
	v_add_f32_e32 v117, v117, v68
	v_add_f32_e32 v116, v116, v69
	v_cvt_pk_bf16_f32 v66, v68, v69
	v_add_f32_e32 v117, v117, v70
	v_add_f32_e32 v116, v116, v71
	v_cvt_pk_bf16_f32 v67, v70, v71
	v_add_f32_e32 v117, v117, v72
	v_add_f32_e32 v116, v116, v73
	v_cvt_pk_bf16_f32 v68, v72, v73
	v_add_f32_e32 v117, v117, v74
	v_add_f32_e32 v116, v116, v75
	v_cvt_pk_bf16_f32 v69, v74, v75
	v_add_f32_e32 v117, v117, v76
	v_add_f32_e32 v116, v116, v77
	v_cvt_pk_bf16_f32 v70, v76, v77
	v_add_f32_e32 v117, v117, v78
	v_add_f32_e32 v116, v116, v79
	v_cvt_pk_bf16_f32 v71, v78, v79
	s_nop 0
	s_nop 0
	v_add_f32_e32 v72, v117, v116
	s_waitcnt lgkmcnt(0)
	v_mfma_f32_32x32x16_bf16 v[0:15], v[80:83], v[64:67], v[0:15]
	s_waitcnt vmcnt(2) lgkmcnt(0)
	s_barrier
	v_add_f32_e32 v150, v150, v72
	v_mfma_f32_32x32x16_bf16 v[16:31], v[84:87], v[64:67], v[16:31]
	v_mfma_f32_32x32x16_bf16 v[0:15], v[88:91], v[68:71], v[0:15]
	v_mfma_f32_32x32x16_bf16 v[16:31], v[92:95], v[68:71], v[16:31]
	v_mfma_f32_32x32x16_bf16 v[32:47], v[112:115], v[108:111], v[32:47]

.LBB0_693:
	s_mul_hi_u32 s5, s48, 0xaaaaaaab
	s_lshr_b32 s5, s5, 1
	s_add_i32 s4, s21, -4
	s_mul_i32 s5, s5, 0xffff4000
	v_lshrrev_b64 v[64:65], s54, v[144:145]
	v_and_b32_e32 v64, 1, v64
	v_cmp_eq_u32_e32 vcc, 1, v64
	v_exp_f32_e32 v48, v48
	v_exp_f32_e32 v49, v49
	v_cndmask_b32_e64 v64, v249, -v154, vcc
	v_mov_b32_e32 v65, v64
	v_mov_b32_e32 v66, v64
	v_mov_b32_e32 v67, v64
	v_mov_b32_e32 v68, v64
	v_mov_b32_e32 v69, v64
	v_mov_b32_e32 v70, v64
	v_mov_b32_e32 v71, v64
	v_mov_b32_e32 v72, v64
	v_mov_b32_e32 v73, v64
	v_mov_b32_e32 v74, v64
	v_mov_b32_e32 v75, v64
	v_mov_b32_e32 v76, v64
	v_mov_b32_e32 v77, v64
	v_mov_b32_e32 v78, v64
	v_mov_b32_e32 v79, v64
	v_exp_f32_e32 v50, v50
	v_exp_f32_e32 v51, v51
	s_waitcnt lgkmcnt(0)
	v_mfma_f32_32x32x16_bf16 v[80:95], v[140:143], v[96:99], v[64:79]
	v_add_u32_e32 v140, s5, v155
	v_exp_f32_e32 v52, v52
	v_exp_f32_e32 v53, v53
	v_exp_f32_e32 v54, v54
	v_exp_f32_e32 v55, v55
	v_exp_f32_e32 v56, v56
	v_exp_f32_e32 v57, v57
	v_mfma_f32_32x32x16_bf16 v[64:79], v[132:135], v[96:99], v[64:79]
	v_exp_f32_e32 v58, v58
	v_exp_f32_e32 v59, v59
	v_exp_f32_e32 v60, v60
	v_exp_f32_e32 v61, v61
	v_exp_f32_e32 v62, v62
	v_exp_f32_e32 v63, v63
	v_mfma_f32_32x32x16_bf16 v[80:95], v[136:139], v[100:103], v[80:95]
	ds_read_b64_tr_b16 v[132:133], v140 offset:8192
	ds_read_b64_tr_b16 v[134:135], v140 offset:8704
	ds_read_b64_tr_b16 v[136:137], v140 offset:9216
	ds_read_b64_tr_b16 v[138:139], v140 offset:9728
	v_mfma_f32_32x32x16_bf16 v[80:95], v[128:131], v[104:107], v[80:95]
	v_mfma_f32_32x32x16_bf16 v[64:79], v[120:123], v[100:103], v[64:79]
	v_mfma_f32_32x32x16_bf16 v[80:95], v[124:127], v[108:111], v[80:95]
	ds_read_b64_tr_b16 v[120:121], v140 offset:12288
	ds_read_b64_tr_b16 v[122:123], v140 offset:12800
	ds_read_b64_tr_b16 v[124:125], v140 offset:13312
	ds_read_b64_tr_b16 v[126:127], v140 offset:13824
	v_add_f32_e32 v128, v215, v48
	v_add_f32_e32 v129, v215, v49
	v_cvt_pk_bf16_f32 v130, v60, v61
	v_add_f32_e32 v128, v128, v50
	v_mfma_f32_32x32x16_bf16 v[64:79], v[116:119], v[104:107], v[64:79]
	v_add_f32_e32 v116, v129, v51
	v_add_f32_e32 v117, v128, v52
	v_cvt_pk_bf16_f32 v118, v52, v53
	v_add_f32_e32 v116, v116, v53
	v_add_f32_e32 v117, v117, v54
	v_cvt_pk_bf16_f32 v119, v54, v55
	v_add_f32_e32 v116, v116, v55
	v_add_f32_e32 v117, v117, v56
	v_cvt_pk_bf16_f32 v128, v56, v57
	v_add_f32_e32 v116, v116, v57
	v_add_f32_e32 v117, v117, v58
	v_cvt_pk_bf16_f32 v129, v58, v59
	v_add_f32_e32 v116, v116, v59
	v_add_f32_e32 v117, v117, v60
	v_cvt_pk_bf16_f32 v131, v62, v63
	v_add_f32_e32 v116, v116, v61
	v_add_f32_e32 v141, v117, v62
	v_cvt_pk_bf16_f32 v117, v50, v51
	v_add_f32_e32 v142, v116, v63
	v_cvt_pk_bf16_f32 v116, v48, v49
	s_waitcnt lgkmcnt(0)
	s_nop 0
	v_mfma_f32_32x32x16_bf16 v[0:15], v[132:135], v[116:119], v[0:15]
	v_exp_f32_e32 v32, v32
	v_exp_f32_e32 v33, v33
	v_exp_f32_e32 v34, v34
	v_exp_f32_e32 v35, v35
	v_exp_f32_e32 v36, v36
	v_exp_f32_e32 v37, v37
	v_exp_f32_e32 v38, v38
	v_mfma_f32_32x32x16_bf16 v[16:31], v[120:123], v[116:119], v[16:31]
	v_exp_f32_e32 v39, v39
	v_exp_f32_e32 v40, v40
	v_exp_f32_e32 v41, v41
	v_exp_f32_e32 v42, v42
	v_exp_f32_e32 v43, v43
	v_exp_f32_e32 v44, v44
	v_exp_f32_e32 v45, v45
	v_mfma_f32_32x32x16_bf16 v[0:15], v[136:139], v[128:131], v[0:15]
	v_exp_f32_e32 v46, v46
	v_exp_f32_e32 v47, v47
	v_mfma_f32_32x32x16_bf16 v[16:31], v[124:127], v[128:131], v[16:31]
	ds_read_b64_tr_b16 v[116:117], v140 offset:10240
	ds_read_b64_tr_b16 v[118:119], v140 offset:10752
	ds_read_b64_tr_b16 v[120:121], v140 offset:14336
	ds_read_b64_tr_b16 v[122:123], v140 offset:14848
	ds_read_b64_tr_b16 v[124:125], v140 offset:11264
	ds_read_b64_tr_b16 v[126:127], v140 offset:11776
	ds_read_b64_tr_b16 v[128:129], v140 offset:15360
	ds_read_b64_tr_b16 v[130:131], v140 offset:15872
	v_add_f32_e32 v132, v141, v32
	v_add_f32_e32 v133, v142, v33
	v_cvt_pk_bf16_f32 v134, v36, v37
	v_add_f32_e32 v132, v132, v34
	v_add_f32_e32 v133, v133, v35
	v_cvt_pk_bf16_f32 v135, v38, v39
	v_add_f32_e32 v132, v132, v36
	v_add_f32_e32 v133, v133, v37
	v_cvt_pk_bf16_f32 v136, v40, v41
	v_add_f32_e32 v132, v132, v38
	v_add_f32_e32 v133, v133, v39
	v_cvt_pk_bf16_f32 v137, v42, v43
	v_add_f32_e32 v132, v132, v40
	v_add_f32_e32 v133, v133, v41
	v_cvt_pk_bf16_f32 v138, v44, v45
	v_add_f32_e32 v132, v132, v42
	v_add_f32_e32 v133, v133, v43
	v_cvt_pk_bf16_f32 v139, v46, v47
	v_add_f32_e32 v132, v132, v44
	v_add_f32_e32 v133, v133, v45
	v_add_f32_e32 v140, v132, v46
	v_add_f32_e32 v141, v133, v47
	v_cvt_pk_bf16_f32 v132, v32, v33
	s_nop 0
	v_cvt_pk_bf16_f32 v133, v34, v35
	v_add_f32_e32 v140, v140, v141
	s_waitcnt lgkmcnt(0)
	v_mfma_f32_32x32x16_bf16 v[0:15], v[116:119], v[132:135], v[0:15]
	s_waitcnt vmcnt(2) lgkmcnt(0)
	s_barrier
	v_add_f32_e32 v150, v150, v140
	s_cmp_ge_u32 s4, s43
	v_mfma_f32_32x32x16_bf16 v[16:31], v[120:123], v[132:135], v[16:31]
	v_mfma_f32_32x32x16_bf16 v[0:15], v[124:127], v[136:139], v[0:15]
	v_mfma_f32_32x32x16_bf16 v[16:31], v[128:131], v[136:139], v[16:31]
	v_mfma_f32_32x32x16_bf16 v[64:79], v[112:115], v[108:111], v[64:79]
	s_cbranch_scc1 .LBB0_688
	s_min_u32 s4, s21, s43
	s_mul_hi_u32 s5, s4, 0x55555556
	s_mul_i32 s5, s5, 3
	s_sub_i32 s5, s4, s5
	s_lshl_b32 s6, s5, 14
	s_mul_i32 s4, s4, 0x50000
	s_mov_b32 s5, s81
	v_lshl_add_u64 v[32:33], v[146:147], 0, s[4:5]
	s_mov_b64 s[4:5], 0xf40
	v_lshl_add_u64 v[32:33], v[32:33], 0, s[4:5]
	s_add_i32 m0, s61, s6
	s_add_i32 s4, s53, s95
	global_load_lds_dwordx4 v[32:33], off
	v_lshl_add_u64 v[32:33], v[148:149], 0, s[80:81]
	s_add_i32 m0, s4, 0x2000
	s_cmp_le_u32 s49, s39
	global_load_lds_dwordx4 v[32:33], off
	s_cbranch_scc1 .LBB0_696
	v_subrev_u32_e32 v32, 64, v156
	v_cmp_lt_i32_e64 s[4:5], -1, v32
	v_cmp_lt_i32_e64 s[6:7], 31, v32
	v_cmp_lt_i32_e32 vcc, 0, v32
	v_cndmask_b32_e64 v80, v249, v80, s[4:5]
	v_cmp_lt_i32_e64 s[4:5], 32, v32
	v_cndmask_b32_e64 v64, v249, v64, s[6:7]
	v_cmp_lt_i32_e64 s[6:7], 1, v32
	v_cndmask_b32_e32 v81, v249, v81, vcc
	v_cmp_lt_i32_e32 vcc, 33, v32
	v_cndmask_b32_e64 v65, v249, v65, s[4:5]
	v_cmp_lt_i32_e64 s[4:5], 2, v32
	v_cndmask_b32_e64 v82, v249, v82, s[6:7]
	v_cmp_lt_i32_e64 s[6:7], 34, v32
	v_cndmask_b32_e32 v66, v249, v66, vcc
	v_cmp_lt_i32_e32 vcc, 7, v32
	v_cndmask_b32_e64 v83, v249, v83, s[4:5]
	v_cmp_lt_i32_e64 s[4:5], 39, v32
	v_cndmask_b32_e64 v67, v249, v67, s[6:7]
	v_cmp_lt_i32_e64 s[6:7], 8, v32
	v_cndmask_b32_e32 v84, v249, v84, vcc
	v_cmp_lt_i32_e32 vcc, 40, v32
	v_cndmask_b32_e64 v68, v249, v68, s[4:5]
	v_cmp_lt_i32_e64 s[4:5], 9, v32
	v_cndmask_b32_e64 v85, v249, v85, s[6:7]
	v_cmp_lt_i32_e64 s[6:7], 41, v32
	v_cndmask_b32_e32 v69, v249, v69, vcc
	v_cmp_lt_i32_e32 vcc, 10, v32
	v_cndmask_b32_e64 v86, v249, v86, s[4:5]
	v_cmp_lt_i32_e64 s[4:5], 42, v32
	v_cndmask_b32_e64 v70, v249, v70, s[6:7]
	v_cmp_lt_i32_e64 s[6:7], 15, v32
	v_cndmask_b32_e32 v87, v249, v87, vcc
	v_cmp_lt_i32_e32 vcc, 47, v32
	v_cndmask_b32_e64 v71, v249, v71, s[4:5]
	v_cmp_lt_i32_e64 s[4:5], 16, v32
	v_cndmask_b32_e64 v88, v249, v88, s[6:7]
	v_cmp_lt_i32_e64 s[6:7], 48, v32
	v_cndmask_b32_e32 v72, v249, v72, vcc
	v_cmp_lt_i32_e32 vcc, 17, v32
	v_cndmask_b32_e64 v89, v249, v89, s[4:5]
	v_cmp_lt_i32_e64 s[4:5], 49, v32
	v_cndmask_b32_e64 v73, v249, v73, s[6:7]
	v_cmp_lt_i32_e64 s[6:7], 18, v32
	v_cndmask_b32_e32 v90, v249, v90, vcc
	v_cmp_lt_i32_e32 vcc, 50, v32
	v_cndmask_b32_e64 v74, v249, v74, s[4:5]
	v_cmp_lt_i32_e64 s[4:5], 23, v32
	v_cndmask_b32_e64 v91, v249, v91, s[6:7]
	v_cmp_lt_i32_e64 s[6:7], 55, v32
	v_cndmask_b32_e32 v75, v249, v75, vcc
	v_cmp_lt_i32_e32 vcc, 24, v32
	v_cndmask_b32_e64 v92, v249, v92, s[4:5]
	v_cmp_lt_i32_e64 s[4:5], 56, v32
	v_cndmask_b32_e64 v76, v249, v76, s[6:7]
	v_cmp_lt_i32_e64 s[6:7], 25, v32
	v_cndmask_b32_e32 v93, v249, v93, vcc
	v_cmp_lt_i32_e32 vcc, 57, v32
	v_cndmask_b32_e64 v77, v249, v77, s[4:5]
	v_cmp_lt_i32_e64 s[4:5], 26, v32
	v_cndmask_b32_e64 v94, v249, v94, s[6:7]
	v_cmp_lt_i32_e64 s[6:7], 58, v32
	v_cndmask_b32_e32 v78, v249, v78, vcc
	s_nop 0
	v_cndmask_b32_e64 v95, v249, v95, s[4:5]
	s_nop 0
	v_cndmask_b32_e64 v79, v249, v79, s[6:7]

; __device__ __forceinline__ int make_tid(int wave0) { int t = wave0 * 64 + (int)__builtin_amdgcn_mbcnt_hi(~0u, __builtin_amdgcn_mbcnt_lo(~0u, 0u)); asm volatile("" : "+v"(t)); return t; }
; #define LAS __attribute__((address_space(3)))
; __device__ __forceinline__ float sum32x(float v) { auto rr = __builtin_amdgcn_permlane32_swap(__float_as_uint(v), __float_as_uint(v), false, false); return __uint_as_float(rr[0]) + __uint_as_float(rr[1]); }
; #define AT_WAITBAR(N) asm volatile("s_waitcnt vmcnt(" #N ") lgkmcnt(0)\n\ts_barrier" ::: "memory")
; template <int DQK, int MODE> ...
;     ...
;     const int tid = make_tid(wave0), lane = tid & 63, r32 = lane & 31, hi = lane >> 5;
;     const int wid = wave0;
;     const int tw0 = t0 + 32 * wid, tq = tw0 + r32;
;     bf16x8 qf[NDS];
; #pragma unroll
;     for (int ds = 0; ds < NDS; ++ds) qf[ds] = *(const bf16x8*)(Qp + (size_t)tq * qs + 16 * ds + 8 * hi);
;     int kt_lo = 0; const int kt_hi = (t0 >> 6) + 3;
;     if (MODE == 1) { const int lo = t0 - 511; kt_lo = lo > 0 ? (lo >> 6) : 0; }
;     unsigned long long selm = 0ull; if (MODE == 2) selm = selp[tq];
;     const int kc0 = wid % CPR, kc1 = (8 + (wid & 3)) % CPR;
;     const bf16_t* ksrc0 = Kp + (size_t)lane * ks + kc0 * 8;
;     const bf16_t* ksrc1 = Kp + (size_t)lane * ks + kc1 * 8;
;     const bf16_t* vsrc = Vp + (size_t)(16 * (wid & 3) + (lane >> 2)) * vs + (wid >> 2) * 32 + (lane & 3) * 8;
;     ...
;     o[0] = f32x16{}; o[1] = f32x16{};
;     float m_run = 0.f, l_run = 0.f; bool init = false;
;     f32x16 negm = f32x16{}; asm volatile("" : "+v"(negm));
;     f32x16 pa0 = f32x16{}, pa1 = f32x16{}, pb0 = f32x16{}, pb1 = f32x16{};
;     bf16x8 kf[2 * NDS];
;     AT_DMAK(kt_lo); AT_DMAV(kt_lo); AT_DMAK(kt_lo + 1); AT_DMAK(kt_lo + 2); AT_DMAV(kt_lo + 1);
;     if (NKW > 1) AT_WAITBAR(3); else AT_WAITBAR(2);
;     ...
;     const float lt = sum32x(l_run);
;     linv = lt > 0.f ? 1.0f / lt : 0.f;
; }
; __device__ __forceinline__ void osave(LAS unsigned char* lds, int tid, const f32x16 (&o)[2], float sc) {
;     LAS float* p = (LAS float*)(lds + OSAVE_OFF) + tid;
; #pragma unroll
;     for (int i = 0; i < 16; ++i) { p[i * 512] = o[0][i] * sc; p[(16 + i) * 512] = o[1][i] * sc; }
; }
; __device__ __forceinline__ float oload(LAS unsigned char* lds, int tid, int i) { return ((LAS float*)(lds + OSAVE_OFF) + tid)[i * 512]; }
.LBB0_698:
	s_lshl_b64 s[2:3], s[22:23], 12
	v_lshl_add_u64 v[156:157], s[2:3], 0, v[214:215]
	s_nop 1
	v_mov_b64_e32 v[32:33], s[10:11]
	v_mad_u64_u32 v[32:33], s[2:3], v156, s85, v[32:33]
	v_mad_u32_u24 v33, v157, s85, v33
	s_mul_i32 s80, s47, 12
	s_waitcnt vmcnt(0) lgkmcnt(0)
	s_barrier
	v_lshl_add_u64 v[158:159], v[32:33], 0, s[80:81]
	global_load_dword v32, v[158:159], off offset:4
	v_mov_b32_e32 v33, v150
	s_nop 1
	v_permlane32_swap_b32_e32 v150, v33
	v_lshl_add_u32 v34, v191, 2, 0
	s_lshl_b32 s2, s46, 1
	v_add_f32_e32 v33, v150, v33
	v_add_u32_e32 v164, 0x10000, v34
	s_add_u32 s4, s45, s2
	v_div_scale_f32 v34, s[2:3], v33, v33, 1.0
	v_rcp_f32_e32 v35, v34
	v_div_scale_f32 v36, vcc, 1.0, v33, 1.0
	v_cmp_lt_f32_e64 s[2:3], 0, v33
	v_fma_f32 v37, -v34, v35, 1.0
	v_fmac_f32_e32 v35, v37, v35
	v_mul_f32_e32 v37, v36, v35
	v_fma_f32 v38, -v34, v37, v36
	v_fmac_f32_e32 v37, v38, v35
	v_fma_f32 v34, -v34, v37, v36
	v_div_fmas_f32 v34, v34, v35, v37
	v_div_fixup_f32 v33, v34, v33, 1.0
	v_cndmask_b32_e64 v33, 0, v33, s[2:3]
	v_mov_b32_e32 v80, v246
	s_addc_u32 s5, s44, 0
	s_mov_b32 s19, s81
	s_mov_b32 s21, s81
	v_mov_b32_e32 v34, v215
	v_mov_b32_e32 v35, v215
	v_mov_b32_e32 v36, v215
	v_mov_b32_e32 v37, v215
	v_mov_b32_e32 v38, v215
	v_mov_b32_e32 v39, v215
	v_mov_b32_e32 v40, v215
	v_mov_b32_e32 v41, v215
	v_mov_b32_e32 v42, v215
	v_mov_b32_e32 v43, v215
	v_mov_b32_e32 v44, v215
	v_mov_b32_e32 v45, v215
	v_mov_b32_e32 v46, v215
	v_mov_b32_e32 v47, v215
	s_waitcnt vmcnt(0)
	v_mul_f32_e32 v32, v32, v33
	v_mul_f32_e32 v0, v0, v32
	v_mul_f32_e32 v1, v1, v32
	v_mul_f32_e32 v16, v16, v32
	v_mul_f32_e32 v17, v17, v32
	v_mul_f32_e32 v2, v2, v32
	v_mul_f32_e32 v18, v18, v32
	v_mul_f32_e32 v3, v3, v32
	v_mul_f32_e32 v19, v19, v32
	v_mul_f32_e32 v4, v4, v32
	v_mul_f32_e32 v20, v20, v32
	v_mul_f32_e32 v5, v5, v32
	v_mul_f32_e32 v21, v21, v32
	v_mul_f32_e32 v6, v6, v32
	v_mul_f32_e32 v22, v22, v32
	v_mul_f32_e32 v7, v7, v32
	v_mul_f32_e32 v23, v23, v32
	v_mul_f32_e32 v8, v8, v32
	v_mul_f32_e32 v24, v24, v32
	v_mul_f32_e32 v9, v9, v32
	v_mul_f32_e32 v25, v25, v32
	v_mul_f32_e32 v10, v10, v32
	v_mul_f32_e32 v26, v26, v32
	v_mul_f32_e32 v11, v11, v32
	v_mul_f32_e32 v27, v27, v32
	v_mul_f32_e32 v12, v12, v32
	v_mul_f32_e32 v28, v28, v32
	v_mul_f32_e32 v13, v13, v32
	v_mul_f32_e32 v29, v29, v32
	v_mul_f32_e32 v14, v14, v32
	v_mul_f32_e32 v30, v30, v32
	v_mul_f32_e32 v15, v15, v32
	v_mul_f32_e32 v31, v31, v32
	ds_write2st64_b32 v164, v0, v1 offset1:8
	ds_write2st64_b32 v164, v16, v17 offset0:128 offset1:136
	ds_write2st64_b32 v164, v2, v3 offset0:16 offset1:24
	ds_write2st64_b32 v164, v18, v19 offset0:144 offset1:152
	ds_write2st64_b32 v164, v4, v5 offset0:32 offset1:40
	ds_write2st64_b32 v164, v20, v21 offset0:160 offset1:168
	ds_write2st64_b32 v164, v6, v7 offset0:48 offset1:56
	ds_write2st64_b32 v164, v22, v23 offset0:176 offset1:184
	ds_write2st64_b32 v164, v8, v9 offset0:64 offset1:72
	ds_write2st64_b32 v164, v24, v25 offset0:192 offset1:200
	ds_write2st64_b32 v164, v10, v11 offset0:80 offset1:88
	ds_write2st64_b32 v164, v26, v27 offset0:208 offset1:216
	ds_write2st64_b32 v164, v12, v13 offset0:96 offset1:104
	ds_write2st64_b32 v164, v28, v29 offset0:224 offset1:232
	ds_write2st64_b32 v164, v14, v15 offset0:112 offset1:120
	ds_write2st64_b32 v164, v30, v31 offset0:240 offset1:248
	v_mov_b64_e32 v[2:3], s[16:17]
	v_and_b32_e32 v0, 31, v80
	v_bfe_u32 v1, v80, 5, 1
	v_or_b32_e32 v4, s39, v0
	v_mad_u64_u32 v[2:3], s[2:3], v4, s65, v[2:3]
	v_lshlrev_b32_e32 v4, 4, v1
	v_mov_b32_e32 v5, v215
	v_lshl_add_u64 v[2:3], v[2:3], 0, v[4:5]
	global_load_dwordx4 v[112:115], v[2:3], off offset:2368
	global_load_dwordx4 v[116:119], v[2:3], off offset:2400
	global_load_dwordx4 v[120:123], v[2:3], off offset:2432
	global_load_dwordx4 v[124:127], v[2:3], off offset:2464
	v_and_b32_e32 v6, 63, v80
	s_add_i32 s2, s40, 0xfffffe01
	v_mul_u32_u24_e32 v2, 0xa00, v6
	s_lshr_b32 s2, s2, 6
	v_lshlrev_b32_e32 v2, 1, v2
	v_mov_b32_e32 v3, v215
	s_cmpk_gt_u32 s40, 0x1ff
	v_lshl_add_u64 v[2:3], s[4:5], 0, v[2:3]
	s_cselect_b32 s16, s2, 0
	v_lshl_add_u64 v[2:3], v[2:3], 0, s[18:19]
	s_mov_b64 s[2:3], 0x1140
	v_lshl_add_u64 v[160:161], v[2:3], 0, s[2:3]
	v_bfe_u32 v2, v80, 2, 4
	v_or_b32_e32 v2, s59, v2
	v_mul_u32_u24_e32 v2, 0xa00, v2
	v_lshlrev_b32_e32 v2, 1, v2
	v_mov_b32_e32 v3, v215
	v_lshl_add_u64 v[2:3], s[4:5], 0, v[2:3]
	v_lshl_add_u64 v[4:5], v[2:3], 0, s[20:21]
	v_lshlrev_b32_e32 v2, 3, v80
	v_and_b32_e32 v2, 24, v2
	v_lshlrev_b32_e32 v6, 1, v2
	v_mov_b32_e32 v7, v215
	v_lshl_add_u64 v[4:5], v[4:5], 0, v[6:7]
	s_mov_b64 s[2:3], 0x1240
	v_lshl_add_u64 v[162:163], v[4:5], 0, s[2:3]
	s_min_u32 s2, s16, s43
	s_mul_i32 s3, s2, 0x56
	s_lshr_b32 s3, s3, 8
	s_mul_i32 s3, s3, 3
	s_sub_i32 s3, s2, s3
	s_and_b32 s3, s3, 0xff
	s_lshl_b32 s3, s3, 14
	s_add_i32 s3, s3, 0
	s_mul_i32 s80, s2, 0x50000
	v_mov_b32_e32 v32, v215
	v_mov_b32_e32 v33, v215
	v_lshl_add_u64 v[4:5], v[160:161], 0, s[80:81]
	s_add_i32 m0, s3, s89
	s_add_i32 s2, s3, s95
	global_load_lds_dwordx4 v[4:5], off
	s_add_i32 m0, s2, 0x2000
	s_or_b32 s2, s16, 1
	s_min_u32 s2, s2, s43
	s_mul_i32 s3, s2, 0x56
	s_lshr_b32 s3, s3, 8
	s_mul_i32 s3, s3, 3
	s_sub_i32 s3, s2, s3
	v_lshl_add_u64 v[4:5], v[162:163], 0, s[80:81]
	s_and_b32 s3, s3, 0xff
	s_mul_i32 s80, s2, 0x50000
	s_or_b32 s2, s16, 2
	s_lshl_b32 s3, s3, 14
	s_min_u32 s2, s2, s43
	s_add_i32 s4, s3, 0
	s_mul_i32 s3, s2, 0x56
	s_lshr_b32 s3, s3, 8
	s_mul_i32 s3, s3, 3
	s_sub_i32 s3, s2, s3
	s_and_b32 s3, s3, 0xff
	global_load_lds_dwordx4 v[4:5], off
	v_lshl_add_u64 v[4:5], v[160:161], 0, s[80:81]
	s_add_i32 m0, s4, s89
	s_lshl_b32 s5, s3, 14
	s_mul_i32 s2, s2, 0x50000
	s_mov_b32 s3, s81
	global_load_lds_dwordx4 v[4:5], off
	v_lshl_add_u64 v[4:5], v[160:161], 0, s[2:3]
	s_add_i32 m0, s61, s5
	s_add_i32 s2, s4, s95
	global_load_lds_dwordx4 v[4:5], off
	s_add_i32 m0, s2, 0x2000
	s_mul_hi_u32 s2, s16, 0x55555556
	s_mul_i32 s2, s2, 3
	s_sub_i32 s2, s16, s2
	v_lshl_add_u64 v[4:5], v[162:163], 0, s[80:81]
	s_lshl_b32 s2, s2, 14
	global_load_lds_dwordx4 v[4:5], off
	s_add_i32 s2, s2, 0
	v_lshlrev_b32_e32 v166, 10, v1
	v_lshlrev_b32_e32 v167, 4, v0
	s_waitcnt vmcnt(2) lgkmcnt(0)
	s_barrier
; #define AT_DMAV(t) do { const int t_ = AT_CL(t); LAS unsigned char* d_ = lds + (t_ % 3) * SLOT + KSL; \
;         __builtin_amdgcn_global_load_lds((const GAS unsigned*)(vsrc + (size_t)t_ * 64 * vs), (LAS unsigned*)(d_ + wid * 1024), 16, 0, 0); } while (0)
; #define AT_WAITBAR(N) asm volatile("s_waitcnt vmcnt(" #N ") lgkmcnt(0)\n\ts_barrier" ::: "memory")
; #define AT_KFRAG(t) do { \
;         LAS unsigned char* Kb_ = lds + ((t) % 3) * SLOT + hi * 1024 + r32 * 16; \
;         _Pragma("unroll") for (int ds = 0; ds < NDS; ++ds) { kf[2 * ds] = *(LAS bf16x8*)(Kb_ + ds * 2048); kf[2 * ds + 1] = *(LAS bf16x8*)(Kb_ + ds * 2048 + 512); } } while (0)
; template <int DQK, int MODE> ...
;     ...
;     AT_DMAK(kt_lo); AT_DMAV(kt_lo); AT_DMAK(kt_lo + 1); AT_DMAK(kt_lo + 2); AT_DMAV(kt_lo + 1);
;     if (NKW > 1) AT_WAITBAR(3); else AT_WAITBAR(2);
;     { AT_KFRAG(kt_lo); asm volatile("s_waitcnt lgkmcnt(0)\n\ts_barrier" ::: "memory");
;       const float b_ = AT_BIAS(kt_lo); AT_QKM(pa0, pa1, AT_SPLAT(b_)); }
;     const int vfo = ((lane >> 4) & 1) * 32 + (lane & 3) * 8 + (4 * hi + ((lane & 15) >> 2)) * 64;
	v_add3_u32 v3, s2, v166, v167
	ds_read_b128 v[4:7], v3
	s_waitcnt vmcnt(2) lgkmcnt(0)
	v_mfma_f32_32x32x16_bf16 v[48:63], v[4:7], v[112:115], 0
	ds_read_b128 v[4:7], v3 offset:512
	s_cmp_gt_u32 s16, s43
	s_waitcnt lgkmcnt(0)
	v_mfma_f32_32x32x16_bf16 v[64:79], v[4:7], v[112:115], 0
	ds_read_b128 v[4:7], v3 offset:2048
	s_waitcnt lgkmcnt(0)
	v_mfma_f32_32x32x16_bf16 v[48:63], v[4:7], v[116:119], v[48:63]
	ds_read_b128 v[4:7], v3 offset:2560
	s_waitcnt lgkmcnt(0)
	v_mfma_f32_32x32x16_bf16 v[64:79], v[4:7], v[116:119], v[64:79]
	ds_read_b128 v[4:7], v3 offset:4096
	s_waitcnt lgkmcnt(0)
	v_mfma_f32_32x32x16_bf16 v[48:63], v[4:7], v[120:123], v[48:63]
	ds_read_b128 v[4:7], v3 offset:4608
	s_waitcnt lgkmcnt(0)
	v_mfma_f32_32x32x16_bf16 v[64:79], v[4:7], v[120:123], v[64:79]
	ds_read_b128 v[4:7], v3 offset:6144
	s_waitcnt lgkmcnt(0)
	v_mfma_f32_32x32x16_bf16 v[48:63], v[4:7], v[124:127], v[48:63]
	ds_read_b128 v[4:7], v3 offset:6656
	s_waitcnt lgkmcnt(0)
	s_barrier
	s_waitcnt lgkmcnt(0)
	v_mfma_f32_32x32x16_bf16 v[64:79], v[4:7], v[124:127], v[64:79]
	s_cbranch_scc1 .LBB0_711
	v_lshlrev_b32_e32 v5, 4, v80
	v_lshlrev_b32_e32 v4, 2, v1
	s_lshl_b32 s2, s16, 14
	v_lshlrev_b32_e32 v1, 8, v1
	v_and_b32_e32 v5, 0xc0, v5
	v_lshlrev_b32_e32 v3, 1, v80
	v_or3_b32 v1, s2, v1, v5
	s_add_i32 s2, s56, s40
	v_and_b32_e32 v3, 32, v3
	v_add_u32_e32 v0, s2, v0
	v_or3_b32 v1, v1, v3, v2
	v_sub_u32_e32 v0, v0, v4
	s_lshl_b32 s20, s16, 6
	v_mov_b32_e32 v171, 0
	v_add3_u32 v168, 0, v166, v167
	s_add_i32 s17, s39, 0xfffffe20
	s_add_i32 s18, s16, 4
	v_add_u32_e32 v169, 0, v1
	s_add_i32 s19, s16, 1
	v_subrev_u32_e32 v170, s20, v0
	s_mov_b64 s[2:3], 0
	v_mov_b32_e32 v165, 0
	v_mov_b32_e32 v16, 0
	v_mov_b32_e32 v17, v171
	v_mov_b32_e32 v18, v171
	v_mov_b32_e32 v19, v171
	v_mov_b32_e32 v20, v171
	v_mov_b32_e32 v21, v171
	v_mov_b32_e32 v22, v171
	v_mov_b32_e32 v23, v171
	v_mov_b32_e32 v24, v171
	v_mov_b32_e32 v25, v171
	v_mov_b32_e32 v26, v171
	v_mov_b32_e32 v27, v171
	v_mov_b32_e32 v28, v171
	v_mov_b32_e32 v29, v171
	v_mov_b32_e32 v30, v171
	v_mov_b32_e32 v31, v171
	v_mov_b32_e32 v0, v171
	v_mov_b32_e32 v1, v171
	v_mov_b32_e32 v2, v171
	v_mov_b32_e32 v3, v171
	v_mov_b32_e32 v4, v171
	v_mov_b32_e32 v5, v171
	v_mov_b32_e32 v6, v171
	v_mov_b32_e32 v7, v171
	v_mov_b32_e32 v8, v171
	v_mov_b32_e32 v9, v171
	v_mov_b32_e32 v10, v171
	v_mov_b32_e32 v11, v171
	v_mov_b32_e32 v12, v171
	v_mov_b32_e32 v13, v171
	v_mov_b32_e32 v14, v171
	v_mov_b32_e32 v15, v171
	s_branch .LBB0_702
.LBB0_700:
	s_mul_hi_u32 s4, s19, 0xaaaaaaab
	s_lshr_b32 s4, s4, 1
	s_mul_i32 s4, s4, 0xffff4000
	s_waitcnt lgkmcnt(0)
	v_mfma_f32_32x32x16_bf16 v[48:63], v[64:67], v[112:115], v[32:47]
	v_add_u32_e32 v188, s4, v169
	v_exp_f32_e32 v96, v96
	v_exp_f32_e32 v97, v97
	v_exp_f32_e32 v98, v98
	v_exp_f32_e32 v99, v99
	v_exp_f32_e32 v100, v100
	v_exp_f32_e32 v101, v101
	v_mfma_f32_32x32x16_bf16 v[64:79], v[152:155], v[112:115], v[32:47]
	ds_read_b64_tr_b16 v[152:153], v188 offset:24576
	ds_read_b64_tr_b16 v[154:155], v188 offset:25088
	ds_read_b64_tr_b16 v[172:173], v188 offset:28672
	ds_read_b64_tr_b16 v[174:175], v188 offset:29184
	ds_read_b64_tr_b16 v[176:177], v188 offset:25600
	ds_read_b64_tr_b16 v[178:179], v188 offset:26112
	ds_read_b64_tr_b16 v[184:185], v188 offset:29696
	ds_read_b64_tr_b16 v[186:187], v188 offset:30208
	v_exp_f32_e32 v102, v102
	v_exp_f32_e32 v103, v103
	v_exp_f32_e32 v104, v104
	v_exp_f32_e32 v105, v105
	v_exp_f32_e32 v106, v106
	v_exp_f32_e32 v107, v107
	v_mfma_f32_32x32x16_bf16 v[48:63], v[140:143], v[116:119], v[48:63]
	v_exp_f32_e32 v108, v108
	v_exp_f32_e32 v109, v109
	v_exp_f32_e32 v110, v110
	v_exp_f32_e32 v111, v111
	s_nop 1
	v_mfma_f32_32x32x16_bf16 v[48:63], v[144:147], v[120:123], v[48:63]
	v_mfma_f32_32x32x16_bf16 v[64:79], v[132:135], v[116:119], v[64:79]
	v_add_f32_e32 v132, v215, v96
	v_add_f32_e32 v133, v215, v97
	v_cvt_pk_bf16_f32 v96, v96, v97
	v_add_f32_e32 v132, v132, v98
	v_add_f32_e32 v133, v133, v99
	v_cvt_pk_bf16_f32 v97, v98, v99
	v_add_f32_e32 v132, v132, v100
	v_mfma_f32_32x32x16_bf16 v[48:63], v[148:151], v[124:127], v[48:63]
	v_add_f32_e32 v133, v133, v101
	v_add_f32_e32 v132, v132, v102
	v_cvt_pk_bf16_f32 v98, v100, v101
	v_add_f32_e32 v133, v133, v103
	v_add_f32_e32 v132, v132, v104
	v_cvt_pk_bf16_f32 v99, v102, v103
	v_add_f32_e32 v133, v133, v105
	v_mfma_f32_32x32x16_bf16 v[64:79], v[136:139], v[120:123], v[64:79]
	v_add_f32_e32 v132, v132, v106
	v_add_f32_e32 v133, v133, v107
	v_cvt_pk_bf16_f32 v100, v104, v105
	v_add_f32_e32 v132, v132, v108
	v_add_f32_e32 v133, v133, v109
	v_cvt_pk_bf16_f32 v101, v106, v107
	v_add_f32_e32 v132, v132, v110
	v_add_f32_e32 v133, v133, v111
	v_cvt_pk_bf16_f32 v102, v108, v109
	v_cvt_pk_bf16_f32 v103, v110, v111
	s_waitcnt lgkmcnt(0)
	v_mfma_f32_32x32x16_bf16 v[16:31], v[152:155], v[96:99], v[16:31]
	v_exp_f32_e32 v80, v80
	v_exp_f32_e32 v81, v81
	v_exp_f32_e32 v82, v82
	v_exp_f32_e32 v83, v83
	v_exp_f32_e32 v84, v84
	v_exp_f32_e32 v85, v85
	v_exp_f32_e32 v86, v86
	v_mfma_f32_32x32x16_bf16 v[0:15], v[172:175], v[96:99], v[0:15]
	v_exp_f32_e32 v87, v87
	v_exp_f32_e32 v88, v88
	v_exp_f32_e32 v89, v89
	v_exp_f32_e32 v90, v90
	v_exp_f32_e32 v91, v91
	v_exp_f32_e32 v92, v92
	v_exp_f32_e32 v93, v93
	v_mfma_f32_32x32x16_bf16 v[16:31], v[176:179], v[100:103], v[16:31]
	v_exp_f32_e32 v94, v94
	v_exp_f32_e32 v95, v95
	v_mfma_f32_32x32x16_bf16 v[0:15], v[184:187], v[100:103], v[0:15]
	ds_read_b64_tr_b16 v[96:97], v188 offset:26624
	ds_read_b64_tr_b16 v[98:99], v188 offset:27136
	ds_read_b64_tr_b16 v[100:101], v188 offset:30720
	ds_read_b64_tr_b16 v[102:103], v188 offset:31232
	ds_read_b64_tr_b16 v[104:105], v188 offset:27648
	ds_read_b64_tr_b16 v[106:107], v188 offset:28160
	ds_read_b64_tr_b16 v[108:109], v188 offset:31744
	ds_read_b64_tr_b16 v[110:111], v188 offset:32256
	v_add_f32_e32 v132, v132, v80
	v_add_f32_e32 v133, v133, v81
	v_cvt_pk_bf16_f32 v80, v80, v81
	v_add_f32_e32 v132, v132, v82
	v_add_f32_e32 v133, v133, v83
	v_cvt_pk_bf16_f32 v81, v82, v83
	v_add_f32_e32 v132, v132, v84
	v_add_f32_e32 v133, v133, v85
	v_cvt_pk_bf16_f32 v82, v84, v85
	v_add_f32_e32 v132, v132, v86
	v_add_f32_e32 v133, v133, v87
	v_cvt_pk_bf16_f32 v83, v86, v87
	v_add_f32_e32 v132, v132, v88
	v_add_f32_e32 v133, v133, v89
	v_cvt_pk_bf16_f32 v84, v88, v89
	v_add_f32_e32 v132, v132, v90
	v_add_f32_e32 v133, v133, v91
	v_cvt_pk_bf16_f32 v85, v90, v91
	v_add_f32_e32 v132, v132, v92
	v_add_f32_e32 v133, v133, v93
	v_cvt_pk_bf16_f32 v86, v92, v93
	v_add_f32_e32 v132, v132, v94
	v_add_f32_e32 v133, v133, v95
	v_cvt_pk_bf16_f32 v87, v94, v95
	s_nop 0
	s_nop 0
	v_add_f32_e32 v88, v132, v133
	s_waitcnt lgkmcnt(0)
	v_mfma_f32_32x32x16_bf16 v[16:31], v[96:99], v[80:83], v[16:31]
	s_waitcnt vmcnt(2) lgkmcnt(0)
	s_barrier
	v_add_f32_e32 v165, v165, v88
	v_mfma_f32_32x32x16_bf16 v[0:15], v[100:103], v[80:83], v[0:15]
	v_mfma_f32_32x32x16_bf16 v[16:31], v[104:107], v[84:87], v[16:31]
	v_mfma_f32_32x32x16_bf16 v[0:15], v[108:111], v[84:87], v[0:15]
	v_mfma_f32_32x32x16_bf16 v[64:79], v[128:131], v[124:127], v[64:79]

.LBB0_706:
	s_mul_hi_u32 s5, s16, 0xaaaaaaab
	s_lshr_b32 s5, s5, 1
	s_add_i32 s4, s18, -4
	s_mul_i32 s5, s5, 0xffff4000
	s_waitcnt lgkmcnt(0)
	v_mfma_f32_32x32x16_bf16 v[96:111], v[80:83], v[112:115], v[32:47]
	v_add_u32_e32 v184, s5, v169
	ds_read_b64_tr_b16 v[172:173], v184 offset:8192
	ds_read_b64_tr_b16 v[174:175], v184 offset:8704
	ds_read_b64_tr_b16 v[176:177], v184 offset:9216
	ds_read_b64_tr_b16 v[178:179], v184 offset:9728
	v_exp_f32_e32 v48, v48
	v_exp_f32_e32 v49, v49
	v_exp_f32_e32 v50, v50
	v_exp_f32_e32 v51, v51
	v_exp_f32_e32 v52, v52
	v_mfma_f32_32x32x16_bf16 v[80:95], v[152:155], v[112:115], v[32:47]
	v_exp_f32_e32 v53, v53
	v_exp_f32_e32 v54, v54
	v_exp_f32_e32 v55, v55
	v_exp_f32_e32 v56, v56
	v_exp_f32_e32 v57, v57
	v_exp_f32_e32 v58, v58
	v_exp_f32_e32 v59, v59
	v_mfma_f32_32x32x16_bf16 v[96:111], v[148:151], v[116:119], v[96:111]
	v_exp_f32_e32 v60, v60
	v_exp_f32_e32 v61, v61
	v_exp_f32_e32 v62, v62
	v_exp_f32_e32 v63, v63
	ds_read_b64_tr_b16 v[148:149], v184 offset:12288
	ds_read_b64_tr_b16 v[150:151], v184 offset:12800
	ds_read_b64_tr_b16 v[152:153], v184 offset:13312
	ds_read_b64_tr_b16 v[154:155], v184 offset:13824
	s_nop 1
	v_mfma_f32_32x32x16_bf16 v[96:111], v[144:147], v[120:123], v[96:111]
	v_add_f32_e32 v144, v215, v49
	v_add_f32_e32 v185, v215, v48
	v_add_f32_e32 v145, v185, v50
	v_add_f32_e32 v144, v144, v51
	s_nop 0
	v_add_f32_e32 v145, v145, v52
	v_mfma_f32_32x32x16_bf16 v[80:95], v[136:139], v[116:119], v[80:95]
	v_add_f32_e32 v144, v144, v53
	v_add_f32_e32 v145, v145, v54
	v_cvt_pk_bf16_f32 v136, v48, v49
	v_add_f32_e32 v144, v144, v55
	v_cvt_pk_bf16_f32 v137, v50, v51
	v_cvt_pk_bf16_f32 v138, v52, v53
	v_cvt_pk_bf16_f32 v139, v54, v55
	v_mfma_f32_32x32x16_bf16 v[96:111], v[140:143], v[124:127], v[96:111]
	v_add_f32_e32 v140, v145, v56
	v_add_f32_e32 v141, v144, v57
	v_cvt_pk_bf16_f32 v142, v60, v61
	v_add_f32_e32 v140, v140, v58
	v_add_f32_e32 v141, v141, v59
	v_cvt_pk_bf16_f32 v143, v62, v63
	v_add_f32_e32 v140, v140, v60
	v_mfma_f32_32x32x16_bf16 v[80:95], v[132:135], v[120:123], v[80:95]
	v_add_f32_e32 v141, v141, v61
	v_add_f32_e32 v185, v140, v62
	v_cvt_pk_bf16_f32 v140, v56, v57
	v_add_f32_e32 v186, v141, v63
	v_cvt_pk_bf16_f32 v141, v58, v59
	s_waitcnt lgkmcnt(0)
	v_mfma_f32_32x32x16_bf16 v[16:31], v[172:175], v[136:139], v[16:31]
	v_exp_f32_e32 v64, v64
	v_exp_f32_e32 v65, v65
	v_exp_f32_e32 v66, v66
	v_exp_f32_e32 v67, v67
	v_exp_f32_e32 v68, v68
	v_exp_f32_e32 v69, v69
	v_exp_f32_e32 v70, v70
	v_mfma_f32_32x32x16_bf16 v[0:15], v[148:151], v[136:139], v[0:15]
	v_exp_f32_e32 v71, v71
	v_exp_f32_e32 v72, v72
	v_exp_f32_e32 v73, v73
	v_exp_f32_e32 v74, v74
	v_exp_f32_e32 v75, v75
	v_exp_f32_e32 v76, v76
	v_exp_f32_e32 v77, v77
	v_mfma_f32_32x32x16_bf16 v[16:31], v[176:179], v[140:143], v[16:31]
	v_exp_f32_e32 v78, v78
	v_exp_f32_e32 v79, v79
	v_mfma_f32_32x32x16_bf16 v[0:15], v[152:155], v[140:143], v[0:15]
	ds_read_b64_tr_b16 v[132:133], v184 offset:10240
	ds_read_b64_tr_b16 v[134:135], v184 offset:10752
	ds_read_b64_tr_b16 v[136:137], v184 offset:14336
	ds_read_b64_tr_b16 v[138:139], v184 offset:14848
	ds_read_b64_tr_b16 v[140:141], v184 offset:11264
	ds_read_b64_tr_b16 v[142:143], v184 offset:11776
	ds_read_b64_tr_b16 v[144:145], v184 offset:15360
	ds_read_b64_tr_b16 v[146:147], v184 offset:15872
	v_add_f32_e32 v148, v185, v64
	v_add_f32_e32 v149, v186, v65
	v_cvt_pk_bf16_f32 v150, v68, v69
	v_add_f32_e32 v148, v148, v66
	v_add_f32_e32 v149, v149, v67
	v_cvt_pk_bf16_f32 v151, v70, v71
	v_add_f32_e32 v148, v148, v68
	v_add_f32_e32 v149, v149, v69
	v_cvt_pk_bf16_f32 v152, v72, v73
	v_add_f32_e32 v148, v148, v70
	v_add_f32_e32 v149, v149, v71
	v_cvt_pk_bf16_f32 v153, v74, v75
	v_add_f32_e32 v148, v148, v72
	v_add_f32_e32 v149, v149, v73
	v_cvt_pk_bf16_f32 v154, v76, v77
	v_add_f32_e32 v148, v148, v74
	v_add_f32_e32 v149, v149, v75
	v_cvt_pk_bf16_f32 v155, v78, v79
	v_add_f32_e32 v148, v148, v76
	v_add_f32_e32 v149, v149, v77
	v_add_f32_e32 v172, v148, v78
	v_add_f32_e32 v173, v149, v79
	v_cvt_pk_bf16_f32 v148, v64, v65
	s_nop 0
	v_cvt_pk_bf16_f32 v149, v66, v67
	v_add_f32_e32 v172, v172, v173
	s_waitcnt lgkmcnt(0)
	v_mfma_f32_32x32x16_bf16 v[16:31], v[132:135], v[148:151], v[16:31]
	s_waitcnt vmcnt(2) lgkmcnt(0)
	s_barrier
	v_add_f32_e32 v165, v165, v172
	s_cmp_ge_u32 s4, s43
	v_mfma_f32_32x32x16_bf16 v[0:15], v[136:139], v[148:151], v[0:15]
	v_mfma_f32_32x32x16_bf16 v[16:31], v[140:143], v[152:155], v[16:31]
	v_mfma_f32_32x32x16_bf16 v[0:15], v[144:147], v[152:155], v[0:15]
	v_mfma_f32_32x32x16_bf16 v[80:95], v[128:131], v[124:127], v[80:95]
	s_cbranch_scc1 .LBB0_701
	s_min_i32 s4, s18, s43
	s_mul_hi_u32 s5, s4, 0xaaaaaaab
	s_lshr_b32 s5, s5, 1
	s_mul_i32 s5, s5, 3
	s_sub_i32 s5, s4, s5
	s_lshl_b32 s6, s5, 14
	s_mul_i32 s4, s4, 0x50000
	s_mov_b32 s5, s81
	v_lshl_add_u64 v[48:49], v[160:161], 0, s[4:5]
	s_add_i32 m0, s61, s6
	s_add_i32 s4, s23, s95
	global_load_lds_dwordx4 v[48:49], off
	v_lshl_add_u64 v[48:49], v[162:163], 0, s[80:81]
	s_add_i32 m0, s4, 0x2000
	s_add_i32 s6, s20, 64
	global_load_lds_dwordx4 v[48:49], off
	s_add_i32 s4, s20, 0x7f
	s_cmp_gt_u32 s4, s39
	s_cselect_b64 s[4:5], -1, 0
	s_cmp_lt_i32 s6, s17
	s_cselect_b64 s[6:7], -1, 0
	s_or_b64 s[4:5], s[4:5], s[6:7]
	s_andn2_b64 vcc, exec, s[4:5]
	s_cbranch_vccnz .LBB0_709
	v_add_u32_e32 v48, 59, v170
	v_add_u32_e32 v49, 27, v170
	v_cmp_gt_u32_e32 vcc, s94, v48
	v_add_u32_e32 v48, 58, v170
	s_nop 0
	v_cndmask_b32_e32 v96, v249, v96, vcc
	v_cmp_gt_u32_e32 vcc, s94, v49
	v_add_u32_e32 v49, 26, v170
	s_nop 0
	v_cndmask_b32_e32 v80, v249, v80, vcc
	v_cmp_gt_u32_e32 vcc, s94, v48
	v_add_u32_e32 v48, 57, v170
	s_nop 0
	v_cndmask_b32_e32 v97, v249, v97, vcc
	v_cmp_gt_u32_e32 vcc, s94, v49
	v_add_u32_e32 v49, 25, v170
	s_nop 0
	v_cndmask_b32_e32 v81, v249, v81, vcc
	v_cmp_gt_u32_e32 vcc, s94, v48
	v_add_u32_e32 v48, 56, v170
	s_nop 0
	v_cndmask_b32_e32 v98, v249, v98, vcc
	v_cmp_gt_u32_e32 vcc, s94, v49
	v_add_u32_e32 v49, 24, v170
	s_nop 0
	v_cndmask_b32_e32 v82, v249, v82, vcc
	v_cmp_gt_u32_e32 vcc, s94, v48
	v_add_u32_e32 v48, 51, v170
	s_nop 0
	v_cndmask_b32_e32 v99, v249, v99, vcc
	v_cmp_gt_u32_e32 vcc, s94, v49
	v_add_u32_e32 v49, 19, v170
	s_nop 0
	v_cndmask_b32_e32 v83, v249, v83, vcc
	v_cmp_gt_u32_e32 vcc, s94, v48
	v_add_u32_e32 v48, 50, v170
	s_nop 0
	v_cndmask_b32_e32 v100, v249, v100, vcc
	v_cmp_gt_u32_e32 vcc, s94, v49
	v_add_u32_e32 v49, 18, v170
	s_nop 0
	v_cndmask_b32_e32 v84, v249, v84, vcc
	v_cmp_gt_u32_e32 vcc, s94, v48
	v_add_u32_e32 v48, 49, v170
	s_nop 0
	v_cndmask_b32_e32 v101, v249, v101, vcc
	v_cmp_gt_u32_e32 vcc, s94, v49
	v_add_u32_e32 v49, 17, v170
	s_nop 0
	v_cndmask_b32_e32 v85, v249, v85, vcc
	v_cmp_gt_u32_e32 vcc, s94, v48
	v_add_u32_e32 v48, 48, v170
	s_nop 0
	v_cndmask_b32_e32 v102, v249, v102, vcc
	v_cmp_gt_u32_e32 vcc, s94, v49
	v_add_u32_e32 v49, 16, v170
	s_nop 0
	v_cndmask_b32_e32 v86, v249, v86, vcc
	v_cmp_gt_u32_e32 vcc, s94, v48
	v_add_u32_e32 v48, 43, v170
	s_nop 0
	v_cndmask_b32_e32 v103, v249, v103, vcc
	v_cmp_gt_u32_e32 vcc, s94, v49
	v_add_u32_e32 v49, 11, v170
	s_nop 0
	v_cndmask_b32_e32 v87, v249, v87, vcc
	v_cmp_gt_u32_e32 vcc, s94, v48
	v_add_u32_e32 v48, 42, v170
	s_nop 0
	v_cndmask_b32_e32 v104, v249, v104, vcc
	v_cmp_gt_u32_e32 vcc, s94, v49
	v_add_u32_e32 v49, 10, v170
	s_nop 0
	v_cndmask_b32_e32 v88, v249, v88, vcc
	v_cmp_gt_u32_e32 vcc, s94, v48
	v_add_u32_e32 v48, 41, v170
	s_nop 0
	v_cndmask_b32_e32 v105, v249, v105, vcc
	v_cmp_gt_u32_e32 vcc, s94, v49
	v_add_u32_e32 v49, 9, v170
	s_nop 0
	v_cndmask_b32_e32 v89, v249, v89, vcc
	v_cmp_gt_u32_e32 vcc, s94, v48
	v_add_u32_e32 v48, 40, v170
	s_nop 0
	v_cndmask_b32_e32 v106, v249, v106, vcc
	v_cmp_gt_u32_e32 vcc, s94, v49
	v_add_u32_e32 v49, 8, v170
	s_nop 0
	v_cndmask_b32_e32 v90, v249, v90, vcc
	v_cmp_gt_u32_e32 vcc, s94, v48
	v_add_u32_e32 v48, 35, v170
	s_nop 0
	v_cndmask_b32_e32 v107, v249, v107, vcc
	v_cmp_gt_u32_e32 vcc, s94, v49
	v_add_u32_e32 v49, 3, v170
	s_nop 0
	v_cndmask_b32_e32 v91, v249, v91, vcc
	v_cmp_gt_u32_e32 vcc, s94, v48
	v_add_u32_e32 v48, 34, v170
	s_nop 0
	v_cndmask_b32_e32 v108, v249, v108, vcc
	v_cmp_gt_u32_e32 vcc, s94, v49
	v_add_u32_e32 v49, 2, v170
	s_nop 0
	v_cndmask_b32_e32 v92, v249, v92, vcc
	v_cmp_gt_u32_e32 vcc, s94, v48
	v_add_u32_e32 v48, 33, v170
	s_nop 0
	v_cndmask_b32_e32 v109, v249, v109, vcc
	v_cmp_gt_u32_e32 vcc, s94, v49
	v_add_u32_e32 v49, 1, v170
	s_nop 0
	v_cndmask_b32_e32 v93, v249, v93, vcc
	v_cmp_gt_u32_e32 vcc, s94, v48
	v_add_u32_e32 v48, 32, v170
	s_nop 0
	v_cndmask_b32_e32 v110, v249, v110, vcc
	v_cmp_gt_u32_e32 vcc, s94, v49
	s_nop 1
	v_cndmask_b32_e32 v94, v249, v94, vcc
	v_cmp_gt_u32_e32 vcc, s94, v48
	s_nop 1
	v_cndmask_b32_e32 v111, v249, v111, vcc
	v_cmp_gt_u32_e32 vcc, s94, v170
	s_nop 1
	v_cndmask_b32_e32 v95, v249, v95, vcc

; __device__ __forceinline__ int make_tid(int wave0) { int t = wave0 * 64 + (int)__builtin_amdgcn_mbcnt_hi(~0u, __builtin_amdgcn_mbcnt_lo(~0u, 0u)); asm volatile("" : "+v"(t)); return t; }
; #define AT_WAITBAR(N) asm volatile("s_waitcnt vmcnt(" #N ") lgkmcnt(0)\n\ts_barrier" ::: "memory")
; template <int DQK, int MODE> ...
;     ...
;     const int tid = make_tid(wave0), lane = tid & 63, r32 = lane & 31, hi = lane >> 5;
;     const int wid = wave0;
;     const int tw0 = t0 + 32 * wid, tq = tw0 + r32;
;     bf16x8 qf[NDS];
; #pragma unroll
;     for (int ds = 0; ds < NDS; ++ds) qf[ds] = *(const bf16x8*)(Qp + (size_t)tq * qs + 16 * ds + 8 * hi);
;     int kt_lo = 0; const int kt_hi = (t0 >> 6) + 3;
;     if (MODE == 1) { const int lo = t0 - 511; kt_lo = lo > 0 ? (lo >> 6) : 0; }
;     unsigned long long selm = 0ull; if (MODE == 2) selm = selp[tq];
;     const int kc0 = wid % CPR, kc1 = (8 + (wid & 3)) % CPR;
;     const bf16_t* ksrc0 = Kp + (size_t)lane * ks + kc0 * 8;
;     const bf16_t* ksrc1 = Kp + (size_t)lane * ks + kc1 * 8;
;     const bf16_t* vsrc = Vp + (size_t)(16 * (wid & 3) + (lane >> 2)) * vs + (wid >> 2) * 32 + (lane & 3) * 8;
;     ...
;     o[0] = f32x16{}; o[1] = f32x16{};
;     float m_run = 0.f, l_run = 0.f; bool init = false;
;     f32x16 negm = f32x16{}; asm volatile("" : "+v"(negm));
;     f32x16 pa0 = f32x16{}, pa1 = f32x16{}, pb0 = f32x16{}, pb1 = f32x16{};
;     bf16x8 kf[2 * NDS];
;     AT_DMAK(kt_lo); AT_DMAV(kt_lo); AT_DMAK(kt_lo + 1); AT_DMAK(kt_lo + 2); AT_DMAV(kt_lo + 1);
;     if (NKW > 1) AT_WAITBAR(3); else AT_WAITBAR(2);
;     { AT_KFRAG(kt_lo); asm volatile("s_waitcnt lgkmcnt(0)\n\ts_barrier" ::: "memory");
;       const float b_ = AT_BIAS(kt_lo); AT_QKM(pa0, pa1, AT_SPLAT(b_)); }
;     const int vfo = ((lane >> 4) & 1) * 32 + (lane & 3) * 8 + (4 * hi + ((lane & 15) >> 2)) * 64;
; __device__ __forceinline__ void attn_phase(LAS unsigned char* lds, int* counter, const bf16_t* __restrict__ P, const bf16_t* __restrict__ Qm, const bf16_t* __restrict__ Kmla, ...
;     ...
;         } else if (r < 64) {
;             const int b = (r - 32) >> 2, h = (r - 32) & 3;
;             const size_t rb = (size_t)b * SEQ;
;             attn_pass<96, 0>(lds, Qm + rb * 384 + h * 96, 384, Kmla + rb * 384 + h * 96, 384, Vmla + rb * 256 + h * 64, 256, t0, nullptr, o, linv, wave0);
.LBB0_713:
	s_and_b64 vcc, exec, s[2:3]
	s_cbranch_vccz .LBB0_727
	s_sub_i32 s2, s41, 32
	s_lshr_b32 s16, s2, 2
	s_and_b32 s19, s41, 3
	s_mul_i32 s5, s16, 0x300000
	s_mul_hi_u32 s4, s16, 0x300000
	s_add_u32 s2, s26, s5
	s_addc_u32 s3, s27, s4
	s_mul_i32 s6, s19, 0xc0
	s_add_u32 s2, s2, s6
	v_mov_b32_e32 v8, v246
	s_addc_u32 s3, s3, 0
	v_mov_b64_e32 v[0:1], s[2:3]
	v_and_b32_e32 v9, 31, v8
	v_bfe_u32 v10, v8, 5, 1
	v_or_b32_e32 v2, s39, v9
	v_mad_u64_u32 v[0:1], s[2:3], v2, s73, v[0:1]
	v_lshlrev_b32_e32 v2, 4, v10
	v_mov_b32_e32 v3, v215
	v_lshl_add_u64 v[0:1], v[0:1], 0, v[2:3]
	global_load_dwordx4 v[112:115], v[0:1], off
	global_load_dwordx4 v[116:119], v[0:1], off offset:32
	global_load_dwordx4 v[120:123], v[0:1], off offset:64
	global_load_dwordx4 v[124:127], v[0:1], off offset:96
	global_load_dwordx4 v[128:131], v[0:1], off offset:128
	global_load_dwordx4 v[132:135], v[0:1], off offset:160
	s_add_u32 s5, s28, s5
	s_addc_u32 s7, s29, s4
	v_and_b32_e32 v4, 63, v8
	s_add_u32 s4, s5, s6
	v_mul_u32_u24_e32 v0, 0x180, v4
	s_addc_u32 s5, s7, 0
	v_lshlrev_b32_e32 v0, 1, v0
	v_mov_b32_e32 v1, v215
	v_readlane_b32 s2, v254, 12
	v_lshl_add_u64 v[0:1], s[4:5], 0, v[0:1]
	s_mov_b32 s4, s2
	v_readlane_b32 s3, v254, 13
	v_writelane_b32 v254, s4, 12
	s_mov_b32 s3, s81
	v_lshl_add_u64 v[184:185], v[0:1], 0, s[2:3]
	v_writelane_b32 v254, s5, 13
	s_mov_b32 s17, s81
	v_readlane_b32 s2, v254, 14
	v_readlane_b32 s3, v254, 15
	s_lshl_b64 s[6:7], s[16:17], 21
	s_mov_b32 s3, s81
	s_add_u32 s6, s30, s6
	v_lshl_add_u64 v[186:187], v[0:1], 0, s[2:3]
	v_lshlrev_b32_e32 v0, 6, v8
	s_addc_u32 s7, s31, s7
	s_lshl_b32 s18, s19, 6
	s_lshl_b32 s19, s19, 7
	v_and_b32_e32 v0, 0xf00, v0
	s_add_u32 s6, s6, s19
	s_mov_b32 s4, s2
	v_or_b32_e32 v0, s62, v0
	s_addc_u32 s7, s7, 0
	v_writelane_b32 v254, s4, 14
	v_lshlrev_b32_e32 v0, 1, v0
	v_mov_b32_e32 v1, v215
	v_lshlrev_b32_e32 v2, 3, v8
	s_add_i32 s2, s63, 0
	v_writelane_b32 v254, s5, 15
	v_lshl_add_u64 v[0:1], s[6:7], 0, v[0:1]
	s_lshl_b32 s80, s60, 1
	v_and_b32_e32 v11, 24, v2
	v_mov_b32_e32 v32, v215
	v_mov_b32_e32 v33, v215
	v_mov_b32_e32 v34, v215
	v_mov_b32_e32 v35, v215
	v_mov_b32_e32 v36, v215
	v_mov_b32_e32 v37, v215
	v_mov_b32_e32 v38, v215
	v_mov_b32_e32 v39, v215
	v_mov_b32_e32 v40, v215
	v_mov_b32_e32 v41, v215
	v_mov_b32_e32 v42, v215
	v_mov_b32_e32 v43, v215
	v_mov_b32_e32 v44, v215
	v_mov_b32_e32 v45, v215
	v_mov_b32_e32 v46, v215
	v_mov_b32_e32 v47, v215
	s_mov_b32 m0, s2
	s_add_i32 s3, s75, 0
	v_lshl_add_u64 v[0:1], v[0:1], 0, s[80:81]
	v_lshlrev_b32_e32 v2, 1, v11
	global_load_lds_dwordx4 v[184:185], off
	s_mov_b32 m0, s3
	v_readlane_b32 s4, v254, 8
	v_lshl_add_u64 v[188:189], v[0:1], 0, v[2:3]
	global_load_lds_dwordx4 v[186:187], off
	s_mov_b32 m0, s4
	s_mov_b64 s[4:5], 0xc000
	global_load_lds_dwordx4 v[188:189], off
	v_lshl_add_u64 v[0:1], v[184:185], 0, s[4:5]
	s_add_i32 m0, s2, 0x5000
	v_lshlrev_b32_e32 v192, 10, v10
	global_load_lds_dwordx4 v[0:1], off
	v_lshl_add_u64 v[0:1], v[186:187], 0, s[4:5]
	s_add_i32 m0, s3, 0x5000
	s_mov_b64 s[4:5], 0x18000
	global_load_lds_dwordx4 v[0:1], off
	v_lshl_add_u64 v[0:1], v[184:185], 0, s[4:5]
	s_add_i32 m0, s2, 0xa000
	v_lshlrev_b32_e32 v193, 4, v9
	global_load_lds_dwordx4 v[0:1], off
	v_lshl_add_u64 v[0:1], v[186:187], 0, s[4:5]
	s_add_i32 m0, s3, 0xa000
	s_mov_b64 s[2:3], 0x8000
	global_load_lds_dwordx4 v[0:1], off
	v_lshl_add_u64 v[0:1], v[188:189], 0, s[2:3]
	s_add_i32 m0, s33, 0x8000
	v_add3_u32 v194, 0, v192, v193
	global_load_lds_dwordx4 v[0:1], off
	s_waitcnt vmcnt(3) lgkmcnt(0)
	s_barrier
	ds_read_b128 v[0:3], v194
	ds_read_b128 v[4:7], v194 offset:512
	s_waitcnt vmcnt(3) lgkmcnt(0)
	v_mfma_f32_32x32x16_bf16 v[48:63], v[0:3], v[112:115], 0
	s_lshr_b32 s2, s40, 6
	v_mov_b32_e32 v197, 0
	s_mov_b32 s19, 4
	s_mov_b32 s20, 1
	s_mov_b32 s21, 0
	s_or_b32 s22, s2, 3
	s_mov_b64 s[2:3], 0
	v_mfma_f32_32x32x16_bf16 v[64:79], v[4:7], v[112:115], 0
	ds_read_b128 v[0:3], v194 offset:2048
	ds_read_b128 v[4:7], v194 offset:2560
	s_movk_i32 s23, 0x7f
	v_mov_b32_e32 v198, 0
	v_mov_b32_e32 v12, v197
	v_mov_b32_e32 v13, v197
	v_mov_b32_e32 v14, v197
	v_mov_b32_e32 v15, v197
	s_waitcnt lgkmcnt(1)
	v_mfma_f32_32x32x16_bf16 v[48:63], v[0:3], v[116:119], v[48:63]
	v_mov_b32_e32 v16, v197
	v_mov_b32_e32 v17, v197
	v_mov_b32_e32 v18, v197
	v_mov_b32_e32 v19, v197
	v_mov_b32_e32 v20, v197
	v_mov_b32_e32 v21, v197
	v_mov_b32_e32 v22, v197
	s_waitcnt lgkmcnt(0)
	v_mfma_f32_32x32x16_bf16 v[64:79], v[4:7], v[116:119], v[64:79]
	ds_read_b128 v[0:3], v194 offset:4096
	ds_read_b128 v[4:7], v194 offset:4608
	v_mov_b32_e32 v23, v197
	v_mov_b32_e32 v24, v197
	v_mov_b32_e32 v25, v197
	v_mov_b32_e32 v26, v197
	v_mov_b32_e32 v27, v197
	v_mov_b32_e32 v28, v197
	s_waitcnt lgkmcnt(1)
	v_mfma_f32_32x32x16_bf16 v[48:63], v[0:3], v[120:123], v[48:63]
	v_mov_b32_e32 v29, v197
	v_mov_b32_e32 v30, v197
	v_mov_b32_e32 v31, v197
	s_waitcnt lgkmcnt(0)
	v_mfma_f32_32x32x16_bf16 v[64:79], v[4:7], v[120:123], v[64:79]
	ds_read_b128 v[0:3], v194 offset:6144
	ds_read_b128 v[4:7], v194 offset:6656
	s_waitcnt lgkmcnt(1)
	v_mfma_f32_32x32x16_bf16 v[48:63], v[0:3], v[124:127], v[48:63]
	s_waitcnt lgkmcnt(0)
	v_mfma_f32_32x32x16_bf16 v[64:79], v[4:7], v[124:127], v[64:79]
	ds_read_b128 v[0:3], v194 offset:8192
	ds_read_b128 v[4:7], v194 offset:8704
	s_waitcnt lgkmcnt(1)
	v_mfma_f32_32x32x16_bf16 v[48:63], v[0:3], v[128:131], v[48:63]
	s_waitcnt lgkmcnt(0)
	v_mfma_f32_32x32x16_bf16 v[64:79], v[4:7], v[128:131], v[64:79]
	ds_read_b128 v[0:3], v194 offset:10240
	ds_read_b128 v[4:7], v194 offset:10752
	s_waitcnt lgkmcnt(0)
	s_barrier
	s_waitcnt lgkmcnt(1)
	v_mfma_f32_32x32x16_bf16 v[48:63], v[0:3], v[132:135], v[48:63]
	v_lshlrev_b32_e32 v2, 4, v8
	v_lshlrev_b32_e32 v0, 1, v8
	v_and_b32_e32 v2, 0xc0, v2
	v_and_b32_e32 v0, 32, v0
	v_lshl_or_b32 v2, v10, 8, v2
	v_or3_b32 v0, v2, v0, v11
	v_lshlrev_b32_e32 v1, 2, v10
	s_waitcnt lgkmcnt(0)
	v_mfma_f32_32x32x16_bf16 v[64:79], v[4:7], v[132:135], v[64:79]
	v_add_u32_e32 v195, 0, v0
	v_add_u32_e32 v0, s39, v9
	v_sub_u32_e32 v196, v0, v1
	v_mov_b32_e32 v0, 0
	v_mov_b32_e32 v1, v197
	v_mov_b32_e32 v2, v197
	v_mov_b32_e32 v3, v197
	v_mov_b32_e32 v4, v197
	v_mov_b32_e32 v5, v197
	v_mov_b32_e32 v6, v197
	v_mov_b32_e32 v7, v197
	v_mov_b32_e32 v8, v197
	v_mov_b32_e32 v9, v197
	v_mov_b32_e32 v10, v197
	v_mov_b32_e32 v11, v197
	s_branch .LBB0_717
.LBB0_715:
	s_mul_hi_u32 s4, s20, 0xaaaaaaab
	s_lshr_b32 s4, s4, 1
	s_mul_i32 s4, s4, 0xffff1000
	s_waitcnt lgkmcnt(0)
	v_mfma_f32_32x32x16_bf16 v[48:63], v[64:67], v[112:115], v[32:47]
	v_exp_f32_e32 v96, v96
	v_exp_f32_e32 v97, v97
	v_exp_f32_e32 v98, v98
	v_exp_f32_e32 v99, v99
	v_exp_f32_e32 v100, v100
	v_exp_f32_e32 v101, v101
	v_exp_f32_e32 v102, v102
	v_mfma_f32_32x32x16_bf16 v[64:79], v[176:179], v[112:115], v[32:47]
	v_add_u32_e32 v176, s4, v195
	v_exp_f32_e32 v103, v103
	v_exp_f32_e32 v104, v104
	v_exp_f32_e32 v105, v105
	v_exp_f32_e32 v106, v106
	v_exp_f32_e32 v107, v107
	v_exp_f32_e32 v108, v108
	v_mfma_f32_32x32x16_bf16 v[48:63], v[168:171], v[116:119], v[48:63]
	v_exp_f32_e32 v109, v109
	v_exp_f32_e32 v110, v110
	v_exp_f32_e32 v111, v111
	v_mfma_f32_32x32x16_bf16 v[48:63], v[172:175], v[120:123], v[48:63]
	ds_read_b64_tr_b16 v[168:169], v176 offset:32768
	ds_read_b64_tr_b16 v[170:171], v176 offset:33280
	ds_read_b64_tr_b16 v[172:173], v176 offset:33792
	ds_read_b64_tr_b16 v[174:175], v176 offset:34304
	v_mfma_f32_32x32x16_bf16 v[64:79], v[152:155], v[116:119], v[64:79]
	v_mfma_f32_32x32x16_bf16 v[48:63], v[164:167], v[124:127], v[48:63]
	v_mfma_f32_32x32x16_bf16 v[64:79], v[148:151], v[120:123], v[64:79]
	v_mfma_f32_32x32x16_bf16 v[48:63], v[160:163], v[128:131], v[48:63]
	v_mfma_f32_32x32x16_bf16 v[64:79], v[144:147], v[124:127], v[64:79]
	v_mfma_f32_32x32x16_bf16 v[48:63], v[156:159], v[132:135], v[48:63]
	ds_read_b64_tr_b16 v[156:157], v176 offset:36864
	ds_read_b64_tr_b16 v[158:159], v176 offset:37376
	ds_read_b64_tr_b16 v[160:161], v176 offset:37888
	ds_read_b64_tr_b16 v[162:163], v176 offset:38400
	v_add_f32_e32 v164, v215, v96
	v_add_f32_e32 v165, v215, v97
	v_cvt_pk_bf16_f32 v96, v96, v97
	v_add_f32_e32 v152, v164, v98
	v_mfma_f32_32x32x16_bf16 v[64:79], v[140:143], v[128:131], v[64:79]
	v_add_f32_e32 v153, v165, v99
	v_add_f32_e32 v152, v152, v100
	v_cvt_pk_bf16_f32 v97, v98, v99
	v_add_f32_e32 v153, v153, v101
	v_add_f32_e32 v152, v152, v102
	v_cvt_pk_bf16_f32 v98, v100, v101
	v_add_f32_e32 v153, v153, v103
	v_add_f32_e32 v152, v152, v104
	v_cvt_pk_bf16_f32 v99, v102, v103
	v_add_f32_e32 v148, v153, v105
	v_add_f32_e32 v149, v152, v106
	v_cvt_pk_bf16_f32 v100, v104, v105
	v_add_f32_e32 v148, v148, v107
	v_add_f32_e32 v149, v149, v108
	v_cvt_pk_bf16_f32 v101, v106, v107
	v_add_f32_e32 v148, v148, v109
	v_add_f32_e32 v149, v149, v110
	v_cvt_pk_bf16_f32 v102, v108, v109
	v_add_f32_e32 v148, v148, v111
	v_cvt_pk_bf16_f32 v103, v110, v111
	s_waitcnt lgkmcnt(0)
	v_mfma_f32_32x32x16_bf16 v[0:15], v[168:171], v[96:99], v[0:15]
	v_exp_f32_e32 v80, v80
	v_exp_f32_e32 v81, v81
	v_exp_f32_e32 v82, v82
	v_exp_f32_e32 v83, v83
	v_exp_f32_e32 v84, v84
	v_exp_f32_e32 v85, v85
	v_exp_f32_e32 v86, v86
	v_mfma_f32_32x32x16_bf16 v[16:31], v[156:159], v[96:99], v[16:31]
	v_exp_f32_e32 v87, v87
	v_exp_f32_e32 v88, v88
	v_exp_f32_e32 v89, v89
	v_exp_f32_e32 v90, v90
	v_exp_f32_e32 v91, v91
	v_exp_f32_e32 v92, v92
	v_exp_f32_e32 v93, v93
	v_mfma_f32_32x32x16_bf16 v[0:15], v[172:175], v[100:103], v[0:15]
	v_exp_f32_e32 v94, v94
	v_exp_f32_e32 v95, v95
	v_mfma_f32_32x32x16_bf16 v[16:31], v[160:163], v[100:103], v[16:31]
	ds_read_b64_tr_b16 v[96:97], v176 offset:34816
	ds_read_b64_tr_b16 v[98:99], v176 offset:35328
	ds_read_b64_tr_b16 v[100:101], v176 offset:38912
	ds_read_b64_tr_b16 v[102:103], v176 offset:39424
	ds_read_b64_tr_b16 v[104:105], v176 offset:35840
	ds_read_b64_tr_b16 v[106:107], v176 offset:36352
	ds_read_b64_tr_b16 v[108:109], v176 offset:39936
	ds_read_b64_tr_b16 v[110:111], v176 offset:40448
	v_add_f32_e32 v140, v149, v80
	v_add_f32_e32 v141, v148, v81
	v_cvt_pk_bf16_f32 v80, v80, v81
	v_add_f32_e32 v140, v140, v82
	v_add_f32_e32 v141, v141, v83
	v_cvt_pk_bf16_f32 v81, v82, v83
	v_add_f32_e32 v140, v140, v84
	v_add_f32_e32 v141, v141, v85
	v_cvt_pk_bf16_f32 v82, v84, v85
	v_add_f32_e32 v140, v140, v86
	v_add_f32_e32 v141, v141, v87
	v_cvt_pk_bf16_f32 v83, v86, v87
	v_add_f32_e32 v140, v140, v88
	v_add_f32_e32 v141, v141, v89
	v_cvt_pk_bf16_f32 v84, v88, v89
	v_add_f32_e32 v140, v140, v90
	v_add_f32_e32 v141, v141, v91
	v_cvt_pk_bf16_f32 v85, v90, v91
	v_add_f32_e32 v140, v140, v92
	v_add_f32_e32 v141, v141, v93
	v_cvt_pk_bf16_f32 v86, v92, v93
	v_add_f32_e32 v140, v140, v94
	v_add_f32_e32 v141, v141, v95
	v_cvt_pk_bf16_f32 v87, v94, v95
	s_nop 0
	s_nop 0
	v_add_f32_e32 v88, v140, v141
	s_waitcnt lgkmcnt(0)
	v_mfma_f32_32x32x16_bf16 v[0:15], v[96:99], v[80:83], v[0:15]
	s_waitcnt vmcnt(3) lgkmcnt(0)
	s_barrier
	v_add_f32_e32 v198, v198, v88
	v_mfma_f32_32x32x16_bf16 v[16:31], v[100:103], v[80:83], v[16:31]
	v_mfma_f32_32x32x16_bf16 v[0:15], v[104:107], v[84:87], v[0:15]
	v_mfma_f32_32x32x16_bf16 v[16:31], v[108:111], v[84:87], v[16:31]
	v_mfma_f32_32x32x16_bf16 v[64:79], v[136:139], v[132:135], v[64:79]

.LBB0_721:
	s_mul_hi_u32 s5, s21, 0xaaaaaaab
	s_lshr_b32 s5, s5, 1
	s_add_i32 s4, s19, -4
	s_mul_i32 s5, s5, 0xffff1000
	s_waitcnt lgkmcnt(0)
	v_mfma_f32_32x32x16_bf16 v[96:111], v[80:83], v[112:115], v[32:47]
	v_exp_f32_e32 v48, v48
	v_exp_f32_e32 v49, v49
	v_exp_f32_e32 v50, v50
	v_exp_f32_e32 v51, v51
	v_exp_f32_e32 v52, v52
	v_exp_f32_e32 v53, v53
	v_exp_f32_e32 v54, v54
	v_mfma_f32_32x32x16_bf16 v[80:95], v[176:179], v[112:115], v[32:47]
	v_add_u32_e32 v176, s5, v195
	v_exp_f32_e32 v55, v55
	v_exp_f32_e32 v56, v56
	v_exp_f32_e32 v57, v57
	v_exp_f32_e32 v58, v58
	v_exp_f32_e32 v59, v59
	v_exp_f32_e32 v60, v60
	v_mfma_f32_32x32x16_bf16 v[96:111], v[168:171], v[116:119], v[96:111]
	v_exp_f32_e32 v61, v61
	v_exp_f32_e32 v62, v62
	v_exp_f32_e32 v63, v63
	v_mfma_f32_32x32x16_bf16 v[96:111], v[172:175], v[120:123], v[96:111]
	ds_read_b64_tr_b16 v[168:169], v176 offset:12288
	ds_read_b64_tr_b16 v[170:171], v176 offset:12800
	ds_read_b64_tr_b16 v[172:173], v176 offset:13312
	ds_read_b64_tr_b16 v[174:175], v176 offset:13824
	v_mfma_f32_32x32x16_bf16 v[80:95], v[152:155], v[116:119], v[80:95]
	v_mfma_f32_32x32x16_bf16 v[96:111], v[164:167], v[124:127], v[96:111]
	v_mfma_f32_32x32x16_bf16 v[80:95], v[148:151], v[120:123], v[80:95]
	v_mfma_f32_32x32x16_bf16 v[96:111], v[160:163], v[128:131], v[96:111]
	v_mfma_f32_32x32x16_bf16 v[80:95], v[144:147], v[124:127], v[80:95]
	v_mfma_f32_32x32x16_bf16 v[96:111], v[156:159], v[132:135], v[96:111]
	ds_read_b64_tr_b16 v[156:157], v176 offset:16384
	ds_read_b64_tr_b16 v[158:159], v176 offset:16896
	ds_read_b64_tr_b16 v[160:161], v176 offset:17408
	ds_read_b64_tr_b16 v[162:163], v176 offset:17920
	v_add_f32_e32 v164, v215, v48
	v_add_f32_e32 v165, v215, v49
	v_cvt_pk_bf16_f32 v144, v48, v49
	v_add_f32_e32 v152, v164, v50
	v_mfma_f32_32x32x16_bf16 v[80:95], v[140:143], v[128:131], v[80:95]
	v_add_f32_e32 v153, v165, v51
	v_add_f32_e32 v152, v152, v52
	v_cvt_pk_bf16_f32 v145, v50, v51
	v_add_f32_e32 v153, v153, v53
	v_add_f32_e32 v152, v152, v54
	v_cvt_pk_bf16_f32 v146, v52, v53
	v_add_f32_e32 v153, v153, v55
	v_add_f32_e32 v152, v152, v56
	v_cvt_pk_bf16_f32 v147, v54, v55
	v_add_f32_e32 v148, v153, v57
	v_add_f32_e32 v149, v152, v58
	v_cvt_pk_bf16_f32 v150, v60, v61
	v_add_f32_e32 v148, v148, v59
	v_add_f32_e32 v149, v149, v60
	v_cvt_pk_bf16_f32 v151, v62, v63
	v_add_f32_e32 v148, v148, v61
	v_add_f32_e32 v164, v149, v62
	v_cvt_pk_bf16_f32 v149, v58, v59
	v_add_f32_e32 v165, v148, v63
	v_cvt_pk_bf16_f32 v148, v56, v57
	s_waitcnt lgkmcnt(0)
	v_mfma_f32_32x32x16_bf16 v[0:15], v[168:171], v[144:147], v[0:15]
	v_exp_f32_e32 v64, v64
	v_exp_f32_e32 v65, v65
	v_exp_f32_e32 v66, v66
	v_exp_f32_e32 v67, v67
	v_exp_f32_e32 v68, v68
	v_exp_f32_e32 v69, v69
	v_exp_f32_e32 v70, v70
	v_mfma_f32_32x32x16_bf16 v[16:31], v[156:159], v[144:147], v[16:31]
	v_exp_f32_e32 v71, v71
	v_exp_f32_e32 v72, v72
	v_exp_f32_e32 v73, v73
	v_exp_f32_e32 v74, v74
	v_exp_f32_e32 v75, v75
	v_exp_f32_e32 v76, v76
	v_exp_f32_e32 v77, v77
	v_mfma_f32_32x32x16_bf16 v[0:15], v[172:175], v[148:151], v[0:15]
	v_exp_f32_e32 v78, v78
	v_exp_f32_e32 v79, v79
	v_mfma_f32_32x32x16_bf16 v[16:31], v[160:163], v[148:151], v[16:31]
	ds_read_b64_tr_b16 v[140:141], v176 offset:14336
	ds_read_b64_tr_b16 v[142:143], v176 offset:14848
	ds_read_b64_tr_b16 v[144:145], v176 offset:18432
	ds_read_b64_tr_b16 v[146:147], v176 offset:18944
	ds_read_b64_tr_b16 v[148:149], v176 offset:15360
	ds_read_b64_tr_b16 v[150:151], v176 offset:15872
	ds_read_b64_tr_b16 v[152:153], v176 offset:19456
	ds_read_b64_tr_b16 v[154:155], v176 offset:19968
	v_add_f32_e32 v156, v164, v64
	v_add_f32_e32 v157, v165, v65
	v_cvt_pk_bf16_f32 v158, v68, v69
	v_add_f32_e32 v156, v156, v66
	v_add_f32_e32 v157, v157, v67
	v_cvt_pk_bf16_f32 v159, v70, v71
	v_add_f32_e32 v156, v156, v68
	v_add_f32_e32 v157, v157, v69
	v_cvt_pk_bf16_f32 v160, v72, v73
	v_add_f32_e32 v156, v156, v70
	v_add_f32_e32 v157, v157, v71
	v_cvt_pk_bf16_f32 v161, v74, v75
	v_add_f32_e32 v156, v156, v72
	v_add_f32_e32 v157, v157, v73
	v_cvt_pk_bf16_f32 v162, v76, v77
	v_add_f32_e32 v156, v156, v74
	v_add_f32_e32 v157, v157, v75
	v_cvt_pk_bf16_f32 v163, v78, v79
	v_add_f32_e32 v156, v156, v76
	v_add_f32_e32 v157, v157, v77
	v_add_f32_e32 v164, v156, v78
	v_add_f32_e32 v165, v157, v79
	v_cvt_pk_bf16_f32 v156, v64, v65
	s_nop 0
	v_cvt_pk_bf16_f32 v157, v66, v67
	v_add_f32_e32 v164, v164, v165
	s_waitcnt lgkmcnt(0)
	v_mfma_f32_32x32x16_bf16 v[0:15], v[140:143], v[156:159], v[0:15]
	s_waitcnt vmcnt(3) lgkmcnt(0)
	s_barrier
	v_add_f32_e32 v198, v198, v164
	s_cmp_ge_u32 s4, s22
	v_mfma_f32_32x32x16_bf16 v[16:31], v[144:147], v[156:159], v[16:31]
	v_mfma_f32_32x32x16_bf16 v[0:15], v[148:151], v[160:163], v[0:15]
	v_mfma_f32_32x32x16_bf16 v[16:31], v[152:155], v[160:163], v[16:31]
	v_mfma_f32_32x32x16_bf16 v[80:95], v[136:139], v[132:135], v[80:95]
	s_cbranch_scc1 .LBB0_716
	s_min_u32 s4, s19, s22
	s_mul_hi_u32 s5, s4, 0x55555556
	s_mul_i32 s5, s5, 3
	s_sub_i32 s5, s4, s5
	s_mulk_i32 s5, 0x5000
	s_add_i32 s5, s5, 0
	s_mul_i32 s80, s4, 0xc000
	v_lshl_add_u64 v[48:49], v[184:185], 0, s[80:81]
	s_add_i32 m0, s5, s63
	s_add_i32 s4, s45, s95
	global_load_lds_dwordx4 v[48:49], off
	v_lshl_add_u64 v[48:49], v[186:187], 0, s[80:81]
	s_add_i32 m0, s5, s75
	s_lshl_b32 s80, s44, 15
	global_load_lds_dwordx4 v[48:49], off
	v_lshl_add_u64 v[48:49], v[188:189], 0, s[80:81]
	s_add_i32 m0, s4, 0x3000
	s_cmp_le_u32 s23, s39
	global_load_lds_dwordx4 v[48:49], off
	s_cbranch_scc1 .LBB0_724
	v_subrev_u32_e32 v48, 64, v196
	v_cmp_lt_i32_e64 s[4:5], -1, v48
	v_cmp_lt_i32_e64 s[6:7], 31, v48
	v_cmp_lt_i32_e32 vcc, 0, v48
	v_cndmask_b32_e64 v96, v249, v96, s[4:5]
	v_cmp_lt_i32_e64 s[4:5], 32, v48
	v_cndmask_b32_e64 v80, v249, v80, s[6:7]
	v_cmp_lt_i32_e64 s[6:7], 1, v48
	v_cndmask_b32_e32 v97, v249, v97, vcc
	v_cmp_lt_i32_e32 vcc, 33, v48
	v_cndmask_b32_e64 v81, v249, v81, s[4:5]
	v_cmp_lt_i32_e64 s[4:5], 2, v48
	v_cndmask_b32_e64 v98, v249, v98, s[6:7]
	v_cmp_lt_i32_e64 s[6:7], 34, v48
	v_cndmask_b32_e32 v82, v249, v82, vcc
	v_cmp_lt_i32_e32 vcc, 7, v48
	v_cndmask_b32_e64 v99, v249, v99, s[4:5]
	v_cmp_lt_i32_e64 s[4:5], 39, v48
	v_cndmask_b32_e64 v83, v249, v83, s[6:7]
	v_cmp_lt_i32_e64 s[6:7], 8, v48
	v_cndmask_b32_e32 v100, v249, v100, vcc
	v_cmp_lt_i32_e32 vcc, 40, v48
	v_cndmask_b32_e64 v84, v249, v84, s[4:5]
	v_cmp_lt_i32_e64 s[4:5], 9, v48
	v_cndmask_b32_e64 v101, v249, v101, s[6:7]
	v_cmp_lt_i32_e64 s[6:7], 41, v48
	v_cndmask_b32_e32 v85, v249, v85, vcc
	v_cmp_lt_i32_e32 vcc, 10, v48
	v_cndmask_b32_e64 v102, v249, v102, s[4:5]
	v_cmp_lt_i32_e64 s[4:5], 42, v48
	v_cndmask_b32_e64 v86, v249, v86, s[6:7]
	v_cmp_lt_i32_e64 s[6:7], 15, v48
	v_cndmask_b32_e32 v103, v249, v103, vcc
	v_cmp_lt_i32_e32 vcc, 47, v48
	v_cndmask_b32_e64 v87, v249, v87, s[4:5]
	v_cmp_lt_i32_e64 s[4:5], 16, v48
	v_cndmask_b32_e64 v104, v249, v104, s[6:7]
	v_cmp_lt_i32_e64 s[6:7], 48, v48
	v_cndmask_b32_e32 v88, v249, v88, vcc
	v_cmp_lt_i32_e32 vcc, 17, v48
	v_cndmask_b32_e64 v105, v249, v105, s[4:5]
	v_cmp_lt_i32_e64 s[4:5], 49, v48
	v_cndmask_b32_e64 v89, v249, v89, s[6:7]
	v_cmp_lt_i32_e64 s[6:7], 18, v48
	v_cndmask_b32_e32 v106, v249, v106, vcc
	v_cmp_lt_i32_e32 vcc, 50, v48
	v_cndmask_b32_e64 v90, v249, v90, s[4:5]
	v_cmp_lt_i32_e64 s[4:5], 23, v48
	v_cndmask_b32_e64 v107, v249, v107, s[6:7]
	v_cmp_lt_i32_e64 s[6:7], 55, v48
	v_cndmask_b32_e32 v91, v249, v91, vcc
	v_cmp_lt_i32_e32 vcc, 24, v48
	v_cndmask_b32_e64 v108, v249, v108, s[4:5]
	v_cmp_lt_i32_e64 s[4:5], 56, v48
	v_cndmask_b32_e64 v92, v249, v92, s[6:7]
	v_cmp_lt_i32_e64 s[6:7], 25, v48
	v_cndmask_b32_e32 v109, v249, v109, vcc
	v_cmp_lt_i32_e32 vcc, 57, v48
	v_cndmask_b32_e64 v93, v249, v93, s[4:5]
	v_cmp_lt_i32_e64 s[4:5], 26, v48
	v_cndmask_b32_e64 v110, v249, v110, s[6:7]
	v_cmp_lt_i32_e64 s[6:7], 58, v48
	v_cndmask_b32_e32 v94, v249, v94, vcc
	s_nop 0
	v_cndmask_b32_e64 v111, v249, v111, s[4:5]
	s_nop 0
	v_cndmask_b32_e64 v95, v249, v95, s[6:7]

; __device__ __forceinline__ int make_tid(int wave0) { int t = wave0 * 64 + (int)__builtin_amdgcn_mbcnt_hi(~0u, __builtin_amdgcn_mbcnt_lo(~0u, 0u)); asm volatile("" : "+v"(t)); return t; }
; #define AT_WAITBAR(N) asm volatile("s_waitcnt vmcnt(" #N ") lgkmcnt(0)\n\ts_barrier" ::: "memory")
; template <int DQK, int MODE> ...
;     ...
;     const int tid = make_tid(wave0), lane = tid & 63, r32 = lane & 31, hi = lane >> 5;
;     const int wid = wave0;
;     const int tw0 = t0 + 32 * wid, tq = tw0 + r32;
;     bf16x8 qf[NDS];
; #pragma unroll
;     for (int ds = 0; ds < NDS; ++ds) qf[ds] = *(const bf16x8*)(Qp + (size_t)tq * qs + 16 * ds + 8 * hi);
;     int kt_lo = 0; const int kt_hi = (t0 >> 6) + 3;
;     if (MODE == 1) { const int lo = t0 - 511; kt_lo = lo > 0 ? (lo >> 6) : 0; }
;     unsigned long long selm = 0ull; if (MODE == 2) selm = selp[tq];
;     const int kc0 = wid % CPR, kc1 = (8 + (wid & 3)) % CPR;
;     const bf16_t* ksrc0 = Kp + (size_t)lane * ks + kc0 * 8;
;     const bf16_t* ksrc1 = Kp + (size_t)lane * ks + kc1 * 8;
;     const bf16_t* vsrc = Vp + (size_t)(16 * (wid & 3) + (lane >> 2)) * vs + (wid >> 2) * 32 + (lane & 3) * 8;
;     ...
;     o[0] = f32x16{}; o[1] = f32x16{};
;     float m_run = 0.f, l_run = 0.f; bool init = false;
;     f32x16 negm = f32x16{}; asm volatile("" : "+v"(negm));
;     f32x16 pa0 = f32x16{}, pa1 = f32x16{}, pb0 = f32x16{}, pb1 = f32x16{};
;     bf16x8 kf[2 * NDS];
;     AT_DMAK(kt_lo); AT_DMAV(kt_lo); AT_DMAK(kt_lo + 1); AT_DMAK(kt_lo + 2); AT_DMAV(kt_lo + 1);
;     if (NKW > 1) AT_WAITBAR(3); else AT_WAITBAR(2);
;     { AT_KFRAG(kt_lo); asm volatile("s_waitcnt lgkmcnt(0)\n\ts_barrier" ::: "memory");
;       const float b_ = AT_BIAS(kt_lo); AT_QKM(pa0, pa1, AT_SPLAT(b_)); }
;     const int vfo = ((lane >> 4) & 1) * 32 + (lane & 3) * 8 + (4 * hi + ((lane & 15) >> 2)) * 64;
; __device__ __forceinline__ void attn_phase(LAS unsigned char* lds, int* counter, const bf16_t* __restrict__ P, const bf16_t* __restrict__ Qm, const bf16_t* __restrict__ Kmla, ...
;     ...
;         if (r < 32) {
;             const int b = r >> 2, h = r & 3;
;             const bf16_t* Pb = P + (size_t)b * SEQ * NPJ;
;             attn_pass<32, 0>(lds, Pb + C_DQ + (2 * h) * 32, NPJ, Pb + C_DK + (2 * h) * 32, NPJ, Pb + C_DV + h * 64, NPJ, t0, nullptr, o, linv, wave0);
.LBB0_728:
	s_andn2_b64 vcc, exec, s[2:3]
	s_cbranch_vccnz .LBB0_668
	s_ashr_i32 s22, s41, 2
	s_mul_i32 s3, s22, 0x1400000
	v_readlane_b32 s4, v254, 48
	s_mul_hi_i32 s2, s22, 0x1400000
	v_readlane_b32 s5, v254, 49
	s_add_u32 s3, s4, s3
	s_addc_u32 s2, s5, s2
	s_lshl_b32 s4, s41, 6
	s_and_b32 s23, s4, 0xc0
	s_lshl_b32 s4, s23, 1
	s_add_u32 s16, s3, s4
	v_mov_b32_e32 v8, v246
	s_addc_u32 s17, s2, 0
	v_mov_b64_e32 v[0:1], s[16:17]
	v_and_b32_e32 v9, 31, v8
	v_bfe_u32 v10, v8, 5, 1
	v_or_b32_e32 v2, s39, v9
	v_mad_u64_u32 v[0:1], s[2:3], v2, s65, v[0:1]
	v_lshlrev_b32_e32 v2, 4, v10
	v_mov_b32_e32 v3, v215
	v_lshl_add_u64 v[0:1], v[0:1], 0, v[2:3]
	global_load_dwordx4 v[112:115], v[0:1], off offset:832
	global_load_dwordx4 v[116:119], v[0:1], off offset:864
	v_and_b32_e32 v2, 63, v8
	v_mul_u32_u24_e32 v0, 0xa00, v2
	v_bfe_u32 v2, v8, 2, 4
	v_or_b32_e32 v2, s59, v2
	v_mul_u32_u24_e32 v2, 0xa00, v2
	v_lshlrev_b32_e32 v0, 1, v0
	v_mov_b32_e32 v1, v215
	v_lshlrev_b32_e32 v2, 1, v2
	v_lshlrev_b32_e32 v4, 3, v8
	v_lshl_add_u64 v[0:1], s[16:17], 0, v[0:1]
	s_lshl_b32 s18, s64, 1
	s_mov_b32 s19, s81
	v_lshl_add_u64 v[2:3], s[16:17], 0, v[2:3]
	s_lshl_b32 s20, s60, 1
	s_mov_b32 s21, s81
	v_and_b32_e32 v11, 24, v4
	v_lshl_add_u64 v[128:129], v[0:1], 0, s[18:19]
	v_lshl_add_u64 v[2:3], v[2:3], 0, s[20:21]
	v_lshlrev_b32_e32 v4, 1, v11
	v_mov_b32_e32 v5, v215
	s_mov_b32 m0, s93
	v_lshl_add_u64 v[0:1], v[128:129], 0, s[76:77]
	v_lshl_add_u64 v[130:131], v[2:3], 0, v[4:5]
	v_mov_b32_e32 v32, v215
	v_mov_b32_e32 v33, v215
	v_mov_b32_e32 v34, v215
	v_mov_b32_e32 v35, v215
	v_mov_b32_e32 v36, v215
	v_mov_b32_e32 v37, v215
	v_mov_b32_e32 v38, v215
	v_mov_b32_e32 v39, v215
	v_mov_b32_e32 v40, v215
	v_mov_b32_e32 v41, v215
	v_mov_b32_e32 v42, v215
	v_mov_b32_e32 v43, v215
	v_mov_b32_e32 v44, v215
	v_mov_b32_e32 v45, v215
	v_mov_b32_e32 v46, v215
	v_mov_b32_e32 v47, v215
	v_readlane_b32 s2, v254, 9
	v_lshl_add_u64 v[2:3], v[130:131], 0, s[0:1]
	global_load_lds_dwordx4 v[0:1], off
	s_mov_b32 m0, s2
	s_mov_b64 s[2:3], 0x50540
	s_add_i32 s41, s93, 0x3000
	global_load_lds_dwordx4 v[2:3], off
	v_lshl_add_u64 v[0:1], v[128:129], 0, s[2:3]
	s_mov_b32 m0, s41
	s_mov_b64 s[2:3], 0xa0540
	s_add_i32 s42, s93, 0x6000
	global_load_lds_dwordx4 v[0:1], off
	v_lshl_add_u64 v[0:1], v[128:129], 0, s[2:3]
	s_mov_b32 m0, s42
	s_mov_b64 s[2:3], 0x50740
	s_add_i32 s43, s33, 0x4000
	global_load_lds_dwordx4 v[0:1], off
	v_lshl_add_u64 v[0:1], v[130:131], 0, s[2:3]
	s_mov_b32 m0, s43
	v_lshlrev_b32_e32 v132, 10, v10
	global_load_lds_dwordx4 v[0:1], off
	v_lshlrev_b32_e32 v133, 4, v9
	s_waitcnt vmcnt(2) lgkmcnt(0)
	s_barrier
	v_add3_u32 v134, 0, v132, v133
	ds_read_b128 v[0:3], v134
	ds_read_b128 v[4:7], v134 offset:512
	s_waitcnt vmcnt(2) lgkmcnt(0)
	v_mfma_f32_32x32x16_bf16 v[48:63], v[0:3], v[112:115], 0
	s_lshr_b32 s2, s40, 6
	v_mov_b32_e32 v137, 0
	s_mov_b32 s19, 1
	s_mov_b32 s21, 4
	s_mov_b32 s44, 0
	s_or_b32 s40, s2, 3
	s_mov_b64 s[2:3], 0
	v_mfma_f32_32x32x16_bf16 v[64:79], v[4:7], v[112:115], 0
	ds_read_b128 v[0:3], v134 offset:2048
	ds_read_b128 v[4:7], v134 offset:2560
	s_waitcnt lgkmcnt(0)
	s_barrier
	s_movk_i32 s45, 0x7f
	v_mov_b32_e32 v138, 0
	v_mov_b32_e32 v12, v137
	v_mov_b32_e32 v13, v137
	v_mov_b32_e32 v14, v137
	s_waitcnt lgkmcnt(1)
	v_mfma_f32_32x32x16_bf16 v[48:63], v[0:3], v[116:119], v[48:63]
	v_lshlrev_b32_e32 v2, 4, v8
	v_lshlrev_b32_e32 v0, 1, v8
	v_and_b32_e32 v2, 0xc0, v2
	v_and_b32_e32 v0, 32, v0
	v_lshl_or_b32 v2, v10, 8, v2
	v_or3_b32 v0, v2, v0, v11
	v_lshlrev_b32_e32 v1, 2, v10
	s_waitcnt lgkmcnt(0)
	v_mfma_f32_32x32x16_bf16 v[64:79], v[4:7], v[116:119], v[64:79]
	v_add_u32_e32 v135, 0, v0
	v_add_u32_e32 v0, s39, v9
	v_sub_u32_e32 v136, v0, v1
	v_mov_b32_e32 v0, 0
	v_mov_b32_e32 v1, v137
	v_mov_b32_e32 v2, v137
	v_mov_b32_e32 v3, v137
	v_mov_b32_e32 v4, v137
	v_mov_b32_e32 v5, v137
	v_mov_b32_e32 v6, v137
	v_mov_b32_e32 v7, v137
	v_mov_b32_e32 v8, v137
	v_mov_b32_e32 v9, v137
	v_mov_b32_e32 v10, v137
	v_mov_b32_e32 v11, v137
	v_mov_b32_e32 v15, v137
	v_mov_b32_e32 v16, v137
	v_mov_b32_e32 v17, v137
	v_mov_b32_e32 v18, v137
	v_mov_b32_e32 v19, v137
	v_mov_b32_e32 v20, v137
	v_mov_b32_e32 v21, v137
	v_mov_b32_e32 v22, v137
	v_mov_b32_e32 v23, v137
	v_mov_b32_e32 v24, v137
	v_mov_b32_e32 v25, v137
	v_mov_b32_e32 v26, v137
	v_mov_b32_e32 v27, v137
	v_mov_b32_e32 v28, v137
	v_mov_b32_e32 v29, v137
	v_mov_b32_e32 v30, v137
	v_mov_b32_e32 v31, v137
	s_branch .LBB0_732
.LBB0_730:
	s_mul_hi_u32 s4, s19, 0xaaaaaaab
	s_lshr_b32 s4, s4, 1
	s_mul_i32 s4, s4, 0xffff7000
	s_waitcnt lgkmcnt(0)
	v_mfma_f32_32x32x16_bf16 v[48:63], v[68:71], v[112:115], v[32:47]
	v_add_u32_e32 v139, s4, v135
	v_exp_f32_e32 v96, v96
	v_exp_f32_e32 v97, v97
	v_exp_f32_e32 v98, v98
	v_exp_f32_e32 v99, v99
	v_exp_f32_e32 v100, v100
	v_exp_f32_e32 v101, v101
	v_exp_f32_e32 v102, v102
	v_exp_f32_e32 v103, v103
	v_mfma_f32_32x32x16_bf16 v[48:63], v[64:67], v[116:119], v[48:63]
	v_exp_f32_e32 v104, v104
	v_exp_f32_e32 v105, v105
	v_exp_f32_e32 v106, v106
	v_exp_f32_e32 v107, v107
	v_exp_f32_e32 v108, v108
	v_exp_f32_e32 v109, v109
	v_exp_f32_e32 v110, v110
	v_exp_f32_e32 v111, v111
	v_mfma_f32_32x32x16_bf16 v[64:79], v[124:127], v[112:115], v[32:47]
	ds_read_b64_tr_b16 v[140:141], v139 offset:16384
	ds_read_b64_tr_b16 v[142:143], v139 offset:16896
	ds_read_b64_tr_b16 v[144:145], v139 offset:17408
	ds_read_b64_tr_b16 v[146:147], v139 offset:17920
	ds_read_b64_tr_b16 v[148:149], v139 offset:20480
	ds_read_b64_tr_b16 v[150:151], v139 offset:20992
	ds_read_b64_tr_b16 v[152:153], v139 offset:21504
	ds_read_b64_tr_b16 v[154:155], v139 offset:22016
	v_add_f32_e32 v124, v215, v96
	v_add_f32_e32 v125, v215, v97
	v_cvt_pk_bf16_f32 v96, v96, v97
	v_add_f32_e32 v124, v124, v98
	v_add_f32_e32 v125, v125, v99
	v_cvt_pk_bf16_f32 v97, v98, v99
	v_add_f32_e32 v124, v124, v100
	v_add_f32_e32 v125, v125, v101
	v_cvt_pk_bf16_f32 v98, v100, v101
	v_add_f32_e32 v124, v124, v102
	v_add_f32_e32 v125, v125, v103
	v_cvt_pk_bf16_f32 v99, v102, v103
	v_add_f32_e32 v124, v124, v104
	v_add_f32_e32 v125, v125, v105
	v_cvt_pk_bf16_f32 v100, v104, v105
	v_add_f32_e32 v124, v124, v106
	v_add_f32_e32 v125, v125, v107
	v_cvt_pk_bf16_f32 v101, v106, v107
	v_add_f32_e32 v124, v124, v108
	v_add_f32_e32 v125, v125, v109
	v_cvt_pk_bf16_f32 v102, v108, v109
	v_add_f32_e32 v124, v124, v110
	v_add_f32_e32 v125, v125, v111
	v_cvt_pk_bf16_f32 v103, v110, v111
	s_waitcnt lgkmcnt(0)
	v_mfma_f32_32x32x16_bf16 v[0:15], v[140:143], v[96:99], v[0:15]
	v_exp_f32_e32 v80, v80
	v_exp_f32_e32 v81, v81
	v_exp_f32_e32 v82, v82
	v_exp_f32_e32 v83, v83
	v_exp_f32_e32 v84, v84
	v_exp_f32_e32 v85, v85
	v_exp_f32_e32 v86, v86
	v_mfma_f32_32x32x16_bf16 v[16:31], v[148:151], v[96:99], v[16:31]
	v_exp_f32_e32 v87, v87
	v_exp_f32_e32 v88, v88
	v_exp_f32_e32 v89, v89
	v_exp_f32_e32 v90, v90
	v_exp_f32_e32 v91, v91
	v_exp_f32_e32 v92, v92
	v_exp_f32_e32 v93, v93
	v_mfma_f32_32x32x16_bf16 v[0:15], v[144:147], v[100:103], v[0:15]
	v_exp_f32_e32 v94, v94
	v_exp_f32_e32 v95, v95
	v_mfma_f32_32x32x16_bf16 v[16:31], v[152:155], v[100:103], v[16:31]
	ds_read_b64_tr_b16 v[96:97], v139 offset:18432
	ds_read_b64_tr_b16 v[98:99], v139 offset:18944
	ds_read_b64_tr_b16 v[100:101], v139 offset:22528
	ds_read_b64_tr_b16 v[102:103], v139 offset:23040
	ds_read_b64_tr_b16 v[104:105], v139 offset:19456
	ds_read_b64_tr_b16 v[106:107], v139 offset:19968
	ds_read_b64_tr_b16 v[108:109], v139 offset:23552
	ds_read_b64_tr_b16 v[110:111], v139 offset:24064
	v_add_f32_e32 v124, v124, v80
	v_add_f32_e32 v125, v125, v81
	v_cvt_pk_bf16_f32 v80, v80, v81
	v_add_f32_e32 v124, v124, v82
	v_add_f32_e32 v125, v125, v83
	v_cvt_pk_bf16_f32 v81, v82, v83
	v_add_f32_e32 v124, v124, v84
	v_add_f32_e32 v125, v125, v85
	v_cvt_pk_bf16_f32 v82, v84, v85
	v_add_f32_e32 v124, v124, v86
	v_add_f32_e32 v125, v125, v87
	v_cvt_pk_bf16_f32 v83, v86, v87
	v_add_f32_e32 v124, v124, v88
	v_add_f32_e32 v125, v125, v89
	v_cvt_pk_bf16_f32 v84, v88, v89
	v_add_f32_e32 v124, v124, v90
	v_add_f32_e32 v125, v125, v91
	v_cvt_pk_bf16_f32 v85, v90, v91
	v_add_f32_e32 v124, v124, v92
	v_add_f32_e32 v125, v125, v93
	v_cvt_pk_bf16_f32 v86, v92, v93
	v_add_f32_e32 v124, v124, v94
	v_add_f32_e32 v125, v125, v95
	v_cvt_pk_bf16_f32 v87, v94, v95
	s_nop 0
	s_nop 0
	v_add_f32_e32 v88, v124, v125
	s_waitcnt lgkmcnt(0)
	v_mfma_f32_32x32x16_bf16 v[0:15], v[96:99], v[80:83], v[0:15]
	s_waitcnt vmcnt(2) lgkmcnt(0)
	s_barrier
	v_add_f32_e32 v138, v138, v88
	v_mfma_f32_32x32x16_bf16 v[16:31], v[100:103], v[80:83], v[16:31]
	v_mfma_f32_32x32x16_bf16 v[0:15], v[104:107], v[84:87], v[0:15]
	v_mfma_f32_32x32x16_bf16 v[16:31], v[108:111], v[84:87], v[16:31]
	v_mfma_f32_32x32x16_bf16 v[64:79], v[120:123], v[116:119], v[64:79]

.LBB0_736:
	s_mul_hi_u32 s5, s44, 0xaaaaaaab
	s_lshr_b32 s5, s5, 1
	s_add_i32 s4, s21, -4
	s_mul_i32 s5, s5, 0xffff7000
	s_waitcnt lgkmcnt(0)
	v_mfma_f32_32x32x16_bf16 v[96:111], v[84:87], v[112:115], v[32:47]
	v_add_u32_e32 v139, s5, v135
	v_exp_f32_e32 v48, v48
	v_exp_f32_e32 v49, v49
	v_exp_f32_e32 v50, v50
	v_exp_f32_e32 v51, v51
	v_exp_f32_e32 v52, v52
	v_exp_f32_e32 v53, v53
	v_exp_f32_e32 v54, v54
	v_exp_f32_e32 v55, v55
	v_mfma_f32_32x32x16_bf16 v[96:111], v[80:83], v[116:119], v[96:111]
	v_exp_f32_e32 v56, v56
	v_exp_f32_e32 v57, v57
	v_exp_f32_e32 v58, v58
	v_exp_f32_e32 v59, v59
	v_exp_f32_e32 v60, v60
	v_exp_f32_e32 v61, v61
	v_exp_f32_e32 v62, v62
	v_exp_f32_e32 v63, v63
	v_mfma_f32_32x32x16_bf16 v[80:95], v[124:127], v[112:115], v[32:47]
	ds_read_b64_tr_b16 v[140:141], v139 offset:4096
	ds_read_b64_tr_b16 v[142:143], v139 offset:4608
	ds_read_b64_tr_b16 v[144:145], v139 offset:5120
	ds_read_b64_tr_b16 v[146:147], v139 offset:5632
	ds_read_b64_tr_b16 v[148:149], v139 offset:8192
	ds_read_b64_tr_b16 v[150:151], v139 offset:8704
	ds_read_b64_tr_b16 v[152:153], v139 offset:9216
	ds_read_b64_tr_b16 v[154:155], v139 offset:9728
	v_add_f32_e32 v124, v215, v48
	v_add_f32_e32 v125, v215, v49
	v_cvt_pk_bf16_f32 v126, v52, v53
	v_add_f32_e32 v124, v124, v50
	v_add_f32_e32 v125, v125, v51
	v_cvt_pk_bf16_f32 v127, v54, v55
	v_add_f32_e32 v124, v124, v52
	v_add_f32_e32 v125, v125, v53
	v_cvt_pk_bf16_f32 v156, v56, v57
	v_add_f32_e32 v124, v124, v54
	v_add_f32_e32 v125, v125, v55
	v_cvt_pk_bf16_f32 v157, v58, v59
	v_add_f32_e32 v124, v124, v56
	v_add_f32_e32 v125, v125, v57
	v_cvt_pk_bf16_f32 v158, v60, v61
	v_add_f32_e32 v124, v124, v58
	v_add_f32_e32 v125, v125, v59
	v_cvt_pk_bf16_f32 v159, v62, v63
	v_add_f32_e32 v124, v124, v60
	v_add_f32_e32 v125, v125, v61
	v_add_f32_e32 v160, v124, v62
	v_add_f32_e32 v161, v125, v63
	v_cvt_pk_bf16_f32 v124, v48, v49
	v_cvt_pk_bf16_f32 v125, v50, v51
	s_waitcnt lgkmcnt(0)
	s_nop 0
	v_mfma_f32_32x32x16_bf16 v[0:15], v[140:143], v[124:127], v[0:15]
	v_exp_f32_e32 v64, v64
	v_exp_f32_e32 v65, v65
	v_exp_f32_e32 v66, v66
	v_exp_f32_e32 v67, v67
	v_exp_f32_e32 v68, v68
	v_exp_f32_e32 v69, v69
	v_exp_f32_e32 v70, v70
	v_mfma_f32_32x32x16_bf16 v[16:31], v[148:151], v[124:127], v[16:31]
	v_exp_f32_e32 v71, v71
	v_exp_f32_e32 v72, v72
	v_exp_f32_e32 v73, v73
	v_exp_f32_e32 v74, v74
	v_exp_f32_e32 v75, v75
	v_exp_f32_e32 v76, v76
	v_exp_f32_e32 v77, v77
	v_mfma_f32_32x32x16_bf16 v[0:15], v[144:147], v[156:159], v[0:15]
	ds_read_b64_tr_b16 v[124:125], v139 offset:6144
	ds_read_b64_tr_b16 v[126:127], v139 offset:6656
	ds_read_b64_tr_b16 v[140:141], v139 offset:10240
	ds_read_b64_tr_b16 v[142:143], v139 offset:10752
	ds_read_b64_tr_b16 v[144:145], v139 offset:7168
	ds_read_b64_tr_b16 v[146:147], v139 offset:7680
	ds_read_b64_tr_b16 v[148:149], v139 offset:11264
	ds_read_b64_tr_b16 v[150:151], v139 offset:11776
	v_exp_f32_e32 v78, v78
	v_exp_f32_e32 v79, v79
	v_add_f32_e32 v139, v160, v64
	v_mfma_f32_32x32x16_bf16 v[16:31], v[152:155], v[156:159], v[16:31]
	v_add_f32_e32 v152, v161, v65
	v_add_f32_e32 v139, v139, v66
	v_cvt_pk_bf16_f32 v153, v66, v67
	v_add_f32_e32 v152, v152, v67
	v_add_f32_e32 v139, v139, v68
	v_cvt_pk_bf16_f32 v154, v68, v69
	v_add_f32_e32 v152, v152, v69
	v_add_f32_e32 v139, v139, v70
	v_cvt_pk_bf16_f32 v155, v70, v71
	v_add_f32_e32 v152, v152, v71
	v_add_f32_e32 v139, v139, v72
	v_cvt_pk_bf16_f32 v156, v72, v73
	v_add_f32_e32 v152, v152, v73
	v_add_f32_e32 v139, v139, v74
	v_cvt_pk_bf16_f32 v157, v74, v75
	v_add_f32_e32 v152, v152, v75
	v_add_f32_e32 v139, v139, v76
	v_cvt_pk_bf16_f32 v158, v76, v77
	v_add_f32_e32 v152, v152, v77
	v_add_f32_e32 v139, v139, v78
	v_cvt_pk_bf16_f32 v159, v78, v79
	v_add_f32_e32 v160, v152, v79
	v_cvt_pk_bf16_f32 v152, v64, v65
	s_nop 0
	s_nop 0
	v_add_f32_e32 v139, v139, v160
	s_waitcnt lgkmcnt(0)
	v_mfma_f32_32x32x16_bf16 v[0:15], v[124:127], v[152:155], v[0:15]
	s_waitcnt vmcnt(2) lgkmcnt(0)
	s_barrier
	v_add_f32_e32 v138, v138, v139
	s_cmp_ge_u32 s4, s40
	v_mfma_f32_32x32x16_bf16 v[16:31], v[140:143], v[152:155], v[16:31]
	v_mfma_f32_32x32x16_bf16 v[0:15], v[144:147], v[156:159], v[0:15]
	v_mfma_f32_32x32x16_bf16 v[16:31], v[148:151], v[156:159], v[16:31]
	v_mfma_f32_32x32x16_bf16 v[80:95], v[120:123], v[116:119], v[80:95]
	s_cbranch_scc1 .LBB0_731
	s_min_u32 s4, s21, s40
	s_mul_hi_u32 s5, s4, 0x55555556
	s_mul_i32 s5, s5, 3
	s_sub_i32 s5, s4, s5
	s_mul_i32 s6, s5, 0x3000
	s_mul_i32 s4, s4, 0x50000
	s_mov_b32 s5, s81
	v_lshl_add_u64 v[48:49], v[128:129], 0, s[4:5]
	v_lshl_add_u64 v[48:49], v[48:49], 0, s[76:77]
	s_add_i32 m0, s93, s6
	s_add_i32 s4, s48, s95
	global_load_lds_dwordx4 v[48:49], off
	v_lshl_add_u64 v[48:49], v[130:131], 0, s[80:81]
	v_lshl_add_u64 v[48:49], v[48:49], 0, s[0:1]
	s_add_i32 m0, s4, 0x1000
	s_cmp_le_u32 s45, s39
	global_load_lds_dwordx4 v[48:49], off
	s_cbranch_scc1 .LBB0_739
	v_subrev_u32_e32 v48, 64, v136
	v_cmp_lt_i32_e64 s[4:5], -1, v48
	v_cmp_lt_i32_e64 s[6:7], 31, v48
	v_cmp_lt_i32_e32 vcc, 0, v48
	v_cndmask_b32_e64 v96, v249, v96, s[4:5]
	v_cmp_lt_i32_e64 s[4:5], 32, v48
	v_cndmask_b32_e64 v80, v249, v80, s[6:7]
	v_cmp_lt_i32_e64 s[6:7], 1, v48
	v_cndmask_b32_e32 v97, v249, v97, vcc
	v_cmp_lt_i32_e32 vcc, 33, v48
	v_cndmask_b32_e64 v81, v249, v81, s[4:5]
	v_cmp_lt_i32_e64 s[4:5], 2, v48
	v_cndmask_b32_e64 v98, v249, v98, s[6:7]
	v_cmp_lt_i32_e64 s[6:7], 34, v48
	v_cndmask_b32_e32 v82, v249, v82, vcc
	v_cmp_lt_i32_e32 vcc, 7, v48
	v_cndmask_b32_e64 v99, v249, v99, s[4:5]
	v_cmp_lt_i32_e64 s[4:5], 39, v48
	v_cndmask_b32_e64 v83, v249, v83, s[6:7]
	v_cmp_lt_i32_e64 s[6:7], 8, v48
	v_cndmask_b32_e32 v100, v249, v100, vcc
	v_cmp_lt_i32_e32 vcc, 40, v48
	v_cndmask_b32_e64 v84, v249, v84, s[4:5]
	v_cmp_lt_i32_e64 s[4:5], 9, v48
	v_cndmask_b32_e64 v101, v249, v101, s[6:7]
	v_cmp_lt_i32_e64 s[6:7], 41, v48
	v_cndmask_b32_e32 v85, v249, v85, vcc
	v_cmp_lt_i32_e32 vcc, 10, v48
	v_cndmask_b32_e64 v102, v249, v102, s[4:5]
	v_cmp_lt_i32_e64 s[4:5], 42, v48
	v_cndmask_b32_e64 v86, v249, v86, s[6:7]
	v_cmp_lt_i32_e64 s[6:7], 15, v48
	v_cndmask_b32_e32 v103, v249, v103, vcc
	v_cmp_lt_i32_e32 vcc, 47, v48
	v_cndmask_b32_e64 v87, v249, v87, s[4:5]
	v_cmp_lt_i32_e64 s[4:5], 16, v48
	v_cndmask_b32_e64 v104, v249, v104, s[6:7]
	v_cmp_lt_i32_e64 s[6:7], 48, v48
	v_cndmask_b32_e32 v88, v249, v88, vcc
	v_cmp_lt_i32_e32 vcc, 17, v48
	v_cndmask_b32_e64 v105, v249, v105, s[4:5]
	v_cmp_lt_i32_e64 s[4:5], 49, v48
	v_cndmask_b32_e64 v89, v249, v89, s[6:7]
	v_cmp_lt_i32_e64 s[6:7], 18, v48
	v_cndmask_b32_e32 v106, v249, v106, vcc
	v_cmp_lt_i32_e32 vcc, 50, v48
	v_cndmask_b32_e64 v90, v249, v90, s[4:5]
	v_cmp_lt_i32_e64 s[4:5], 23, v48
	v_cndmask_b32_e64 v107, v249, v107, s[6:7]
	v_cmp_lt_i32_e64 s[6:7], 55, v48
	v_cndmask_b32_e32 v91, v249, v91, vcc
	v_cmp_lt_i32_e32 vcc, 24, v48
	v_cndmask_b32_e64 v108, v249, v108, s[4:5]
	v_cmp_lt_i32_e64 s[4:5], 56, v48
	v_cndmask_b32_e64 v92, v249, v92, s[6:7]
	v_cmp_lt_i32_e64 s[6:7], 25, v48
	v_cndmask_b32_e32 v109, v249, v109, vcc
	v_cmp_lt_i32_e32 vcc, 57, v48
	v_cndmask_b32_e64 v93, v249, v93, s[4:5]
	v_cmp_lt_i32_e64 s[4:5], 26, v48
	v_cndmask_b32_e64 v110, v249, v110, s[6:7]
	v_cmp_lt_i32_e64 s[6:7], 58, v48
	v_cndmask_b32_e32 v94, v249, v94, vcc
	s_nop 0
	v_cndmask_b32_e64 v111, v249, v111, s[4:5]
	s_nop 0
	v_cndmask_b32_e64 v95, v249, v95, s[6:7]

; #define LAS __attribute__((address_space(3)))
; __device__ __forceinline__ float sum32x(float v) { auto rr = __builtin_amdgcn_permlane32_swap(__float_as_uint(v), __float_as_uint(v), false, false); return __uint_as_float(rr[0]) + __uint_as_float(rr[1]); }
; template <int DQK, int MODE> ...
;     ...
;     const float lt = sum32x(l_run);
;     linv = lt > 0.f ? 1.0f / lt : 0.f;
; }
; __device__ __forceinline__ void osave(LAS unsigned char* lds, int tid, const f32x16 (&o)[2], float sc) {
;     LAS float* p = (LAS float*)(lds + OSAVE_OFF) + tid;
; #pragma unroll
;     for (int i = 0; i < 16; ++i) { p[i * 512] = o[0][i] * sc; p[(16 + i) * 512] = o[1][i] * sc; }
; }
; __device__ __forceinline__ float oload(LAS unsigned char* lds, int tid, int i) { return ((LAS float*)(lds + OSAVE_OFF) + tid)[i * 512]; }
; __device__ __forceinline__ void attn_phase(LAS unsigned char* lds, int* counter, const bf16_t* __restrict__ P, const bf16_t* __restrict__ Qm, const bf16_t* __restrict__ Kmla, ...
;     ...
;             osave(lds, tid, o, linv);
;             attn_pass<32, 0>(lds, Pb + C_DQ + (2 * h + 1) * 32, NPJ, Pb + C_DK + (2 * h + 1) * 32, NPJ, Pb + C_DV + h * 64, NPJ, t0, nullptr, o, linv, wave0);
.LBB0_741:
	v_mov_b32_e32 v32, v138
	s_nop 1
	v_permlane32_swap_b32_e32 v138, v32
	v_add_f32_e32 v32, v138, v32
	v_div_scale_f32 v33, s[2:3], v32, v32, 1.0
	v_rcp_f32_e32 v34, v33
	s_waitcnt vmcnt(0) lgkmcnt(0)
	s_barrier
	s_mov_b32 s19, s81
	s_mov_b32 s21, s81
	v_fma_f32 v35, -v33, v34, 1.0
	v_fmac_f32_e32 v34, v35, v34
	v_div_scale_f32 v35, vcc, 1.0, v32, 1.0
	v_mul_f32_e32 v36, v35, v34
	v_fma_f32 v37, -v33, v36, v35
	v_fmac_f32_e32 v36, v37, v34
	v_fma_f32 v33, -v33, v36, v35
	v_div_fmas_f32 v33, v33, v34, v36
	v_div_fixup_f32 v33, v33, v32, 1.0
	v_cmp_lt_f32_e32 vcc, 0, v32
	s_mov_b32 m0, s93
	v_mov_b32_e32 v34, v215
	v_cndmask_b32_e32 v32, 0, v33, vcc
	v_lshl_add_u32 v33, v191, 2, 0
	v_add_u32_e32 v132, 0x10000, v33
	v_mul_f32_e32 v0, v0, v32
	v_mul_f32_e32 v1, v1, v32
	v_mul_f32_e32 v16, v16, v32
	ds_write2st64_b32 v132, v0, v1 offset1:8
	v_mul_f32_e32 v0, v17, v32
	ds_write2st64_b32 v132, v16, v0 offset0:128 offset1:136
	v_mul_f32_e32 v0, v2, v32
	v_mul_f32_e32 v2, v3, v32
	v_mul_f32_e32 v1, v18, v32
	ds_write2st64_b32 v132, v0, v2 offset0:16 offset1:24
	v_mul_f32_e32 v0, v19, v32
	ds_write2st64_b32 v132, v1, v0 offset0:144 offset1:152
	v_mul_f32_e32 v0, v4, v32
	v_mul_f32_e32 v2, v5, v32
	v_mul_f32_e32 v1, v20, v32
	ds_write2st64_b32 v132, v0, v2 offset0:32 offset1:40
	v_mul_f32_e32 v0, v21, v32
	ds_write2st64_b32 v132, v1, v0 offset0:160 offset1:168
	v_mul_f32_e32 v0, v6, v32
	v_mul_f32_e32 v2, v7, v32
	v_mul_f32_e32 v1, v22, v32
	ds_write2st64_b32 v132, v0, v2 offset0:48 offset1:56
	v_mul_f32_e32 v0, v23, v32
	ds_write2st64_b32 v132, v1, v0 offset0:176 offset1:184
	v_mul_f32_e32 v0, v8, v32
	v_mul_f32_e32 v2, v9, v32
	v_mul_f32_e32 v1, v24, v32
	ds_write2st64_b32 v132, v0, v2 offset0:64 offset1:72
	v_mul_f32_e32 v0, v25, v32
	ds_write2st64_b32 v132, v1, v0 offset0:192 offset1:200
	v_mul_f32_e32 v0, v10, v32
	v_mul_f32_e32 v2, v11, v32
	v_mul_f32_e32 v1, v26, v32
	ds_write2st64_b32 v132, v0, v2 offset0:80 offset1:88
	v_mul_f32_e32 v0, v27, v32
	ds_write2st64_b32 v132, v1, v0 offset0:208 offset1:216
	v_mul_f32_e32 v0, v12, v32
	v_mul_f32_e32 v2, v13, v32
	v_mul_f32_e32 v1, v28, v32
	ds_write2st64_b32 v132, v0, v2 offset0:96 offset1:104
	v_mul_f32_e32 v0, v29, v32
	ds_write2st64_b32 v132, v1, v0 offset0:224 offset1:232
	v_mul_f32_e32 v0, v14, v32
	v_mul_f32_e32 v2, v15, v32
	v_mul_f32_e32 v1, v30, v32
	ds_write2st64_b32 v132, v0, v2 offset0:112 offset1:120
	v_mul_f32_e32 v0, v31, v32
	v_mov_b32_e32 v8, v246
	ds_write2st64_b32 v132, v1, v0 offset0:240 offset1:248
	v_mov_b64_e32 v[0:1], s[16:17]
	v_and_b32_e32 v9, 31, v8
	v_bfe_u32 v10, v8, 5, 1
	v_or_b32_e32 v2, s39, v9
	v_mad_u64_u32 v[0:1], s[2:3], v2, s65, v[0:1]
	v_lshlrev_b32_e32 v2, 4, v10
	v_mov_b32_e32 v3, v215
	v_lshl_add_u64 v[0:1], v[0:1], 0, v[2:3]
	global_load_dwordx4 v[112:115], v[0:1], off offset:896
	global_load_dwordx4 v[116:119], v[0:1], off offset:928
	v_and_b32_e32 v2, 63, v8
	v_mul_u32_u24_e32 v0, 0xa00, v2
	v_bfe_u32 v2, v8, 2, 4
	v_or_b32_e32 v2, s59, v2
	v_mul_u32_u24_e32 v2, 0xa00, v2
	v_lshlrev_b32_e32 v0, 1, v0
	v_mov_b32_e32 v1, v215
	v_lshlrev_b32_e32 v2, 1, v2
	v_lshlrev_b32_e32 v4, 3, v8
	v_lshl_add_u64 v[0:1], s[16:17], 0, v[0:1]
	v_lshl_add_u64 v[2:3], s[16:17], 0, v[2:3]
	v_and_b32_e32 v11, 24, v4
	v_lshl_add_u64 v[128:129], v[0:1], 0, s[18:19]
	v_lshl_add_u64 v[2:3], v[2:3], 0, s[20:21]
	v_lshlrev_b32_e32 v4, 1, v11
	v_mov_b32_e32 v5, v215
	v_lshl_add_u64 v[0:1], v[128:129], 0, s[90:91]
	v_lshl_add_u64 v[130:131], v[2:3], 0, v[4:5]
	v_mov_b32_e32 v32, v215
	v_mov_b32_e32 v33, v215
	v_mov_b32_e32 v35, v215
	v_mov_b32_e32 v36, v215
	v_mov_b32_e32 v37, v215
	v_mov_b32_e32 v38, v215
	v_mov_b32_e32 v39, v215
	v_mov_b32_e32 v40, v215
	v_mov_b32_e32 v41, v215
	v_mov_b32_e32 v42, v215
	v_mov_b32_e32 v43, v215
	v_mov_b32_e32 v44, v215
	v_mov_b32_e32 v45, v215
	v_mov_b32_e32 v46, v215
	v_mov_b32_e32 v47, v215
	v_readlane_b32 s2, v254, 9
	v_lshl_add_u64 v[2:3], v[130:131], 0, s[0:1]
	global_load_lds_dwordx4 v[0:1], off
	s_mov_b32 m0, s2
	s_mov_b64 s[2:3], 0x50580
	global_load_lds_dwordx4 v[2:3], off
	v_lshl_add_u64 v[0:1], v[128:129], 0, s[2:3]
	s_mov_b32 m0, s41
	s_mov_b64 s[2:3], 0xa0580
	global_load_lds_dwordx4 v[0:1], off
	v_lshl_add_u64 v[0:1], v[128:129], 0, s[2:3]
	s_mov_b32 m0, s42
	s_mov_b64 s[2:3], 0x50740
	global_load_lds_dwordx4 v[0:1], off
	v_lshl_add_u64 v[0:1], v[130:131], 0, s[2:3]
	s_mov_b32 m0, s43
	v_lshlrev_b32_e32 v133, 10, v10
	global_load_lds_dwordx4 v[0:1], off
	v_lshlrev_b32_e32 v134, 4, v9
	s_waitcnt vmcnt(2) lgkmcnt(0)
	s_barrier
	v_add3_u32 v135, 0, v133, v134
	ds_read_b128 v[0:3], v135
	ds_read_b128 v[4:7], v135 offset:512
	s_waitcnt vmcnt(2) lgkmcnt(0)
	v_mfma_f32_32x32x16_bf16 v[48:63], v[0:3], v[112:115], 0
	v_mov_b32_e32 v138, 0
	s_mov_b32 s16, 0
	s_mov_b32 s17, 4
	s_mov_b32 s18, 1
	s_mov_b64 s[2:3], 0
	s_movk_i32 s19, 0x7f
	v_mov_b32_e32 v139, 0
	v_mfma_f32_32x32x16_bf16 v[64:79], v[4:7], v[112:115], 0
	ds_read_b128 v[0:3], v135 offset:2048
	ds_read_b128 v[4:7], v135 offset:2560
	s_waitcnt lgkmcnt(0)
	s_barrier
	v_mov_b32_e32 v12, v138
	v_mov_b32_e32 v13, v138
	v_mov_b32_e32 v14, v138
	v_mov_b32_e32 v15, v138
	v_mov_b32_e32 v16, v138
	s_waitcnt lgkmcnt(1)
	v_mfma_f32_32x32x16_bf16 v[48:63], v[0:3], v[116:119], v[48:63]
	v_lshlrev_b32_e32 v2, 4, v8
	v_lshlrev_b32_e32 v0, 1, v8
	v_and_b32_e32 v2, 0xc0, v2
	v_and_b32_e32 v0, 32, v0
	v_lshl_or_b32 v2, v10, 8, v2
	v_or3_b32 v0, v2, v0, v11
	v_lshlrev_b32_e32 v1, 2, v10
	s_waitcnt lgkmcnt(0)
	v_mfma_f32_32x32x16_bf16 v[64:79], v[4:7], v[116:119], v[64:79]
	v_add_u32_e32 v136, 0, v0
	v_add_u32_e32 v0, s39, v9
	v_sub_u32_e32 v137, v0, v1
	v_mov_b32_e32 v0, 0
	v_mov_b32_e32 v1, v138
	v_mov_b32_e32 v2, v138
	v_mov_b32_e32 v3, v138
	v_mov_b32_e32 v4, v138
	v_mov_b32_e32 v5, v138
	v_mov_b32_e32 v6, v138
	v_mov_b32_e32 v7, v138
	v_mov_b32_e32 v8, v138
	v_mov_b32_e32 v9, v138
	v_mov_b32_e32 v10, v138
	v_mov_b32_e32 v11, v138
	v_mov_b32_e32 v17, v138
	v_mov_b32_e32 v18, v138
	v_mov_b32_e32 v19, v138
	v_mov_b32_e32 v20, v138
	v_mov_b32_e32 v21, v138
	v_mov_b32_e32 v22, v138
	v_mov_b32_e32 v23, v138
	v_mov_b32_e32 v24, v138
	v_mov_b32_e32 v25, v138
	v_mov_b32_e32 v26, v138
	v_mov_b32_e32 v27, v138
	v_mov_b32_e32 v28, v138
	v_mov_b32_e32 v29, v138
	v_mov_b32_e32 v30, v138
	v_mov_b32_e32 v31, v138
	s_branch .LBB0_744
.LBB0_742:
	s_mul_hi_u32 s4, s18, 0xaaaaaaab
	s_lshr_b32 s4, s4, 1
	s_mul_i32 s4, s4, 0xffff7000
	s_waitcnt lgkmcnt(0)
	v_mfma_f32_32x32x16_bf16 v[48:63], v[68:71], v[112:115], v[32:47]
	v_add_u32_e32 v156, s4, v136
	v_exp_f32_e32 v96, v96
	v_exp_f32_e32 v97, v97
	v_exp_f32_e32 v98, v98
	v_exp_f32_e32 v99, v99
	v_exp_f32_e32 v100, v100
	v_exp_f32_e32 v101, v101
	v_exp_f32_e32 v102, v102
	v_exp_f32_e32 v103, v103
	v_mfma_f32_32x32x16_bf16 v[48:63], v[64:67], v[116:119], v[48:63]
	v_exp_f32_e32 v104, v104
	v_exp_f32_e32 v105, v105
	v_exp_f32_e32 v106, v106
	v_exp_f32_e32 v107, v107
	v_exp_f32_e32 v108, v108
	v_exp_f32_e32 v109, v109
	v_exp_f32_e32 v110, v110
	v_exp_f32_e32 v111, v111
	v_mfma_f32_32x32x16_bf16 v[64:79], v[124:127], v[112:115], v[32:47]
	ds_read_b64_tr_b16 v[140:141], v156 offset:16384
	ds_read_b64_tr_b16 v[142:143], v156 offset:16896
	ds_read_b64_tr_b16 v[144:145], v156 offset:17408
	ds_read_b64_tr_b16 v[146:147], v156 offset:17920
	ds_read_b64_tr_b16 v[148:149], v156 offset:20480
	ds_read_b64_tr_b16 v[150:151], v156 offset:20992
	ds_read_b64_tr_b16 v[152:153], v156 offset:21504
	ds_read_b64_tr_b16 v[154:155], v156 offset:22016
	v_add_f32_e32 v124, v215, v96
	v_add_f32_e32 v125, v215, v97
	v_cvt_pk_bf16_f32 v96, v96, v97
	v_add_f32_e32 v124, v124, v98
	v_add_f32_e32 v125, v125, v99
	v_cvt_pk_bf16_f32 v97, v98, v99
	v_add_f32_e32 v124, v124, v100
	v_add_f32_e32 v125, v125, v101
	v_cvt_pk_bf16_f32 v98, v100, v101
	v_add_f32_e32 v124, v124, v102
	v_add_f32_e32 v125, v125, v103
	v_cvt_pk_bf16_f32 v99, v102, v103
	v_add_f32_e32 v124, v124, v104
	v_add_f32_e32 v125, v125, v105
	v_cvt_pk_bf16_f32 v100, v104, v105
	v_add_f32_e32 v124, v124, v106
	v_add_f32_e32 v125, v125, v107
	v_cvt_pk_bf16_f32 v101, v106, v107
	v_add_f32_e32 v124, v124, v108
	v_add_f32_e32 v125, v125, v109
	v_cvt_pk_bf16_f32 v102, v108, v109
	v_add_f32_e32 v124, v124, v110
	v_add_f32_e32 v125, v125, v111
	v_cvt_pk_bf16_f32 v103, v110, v111
	s_waitcnt lgkmcnt(0)
	v_mfma_f32_32x32x16_bf16 v[0:15], v[140:143], v[96:99], v[0:15]
	v_exp_f32_e32 v80, v80
	v_exp_f32_e32 v81, v81
	v_exp_f32_e32 v82, v82
	v_exp_f32_e32 v83, v83
	v_exp_f32_e32 v84, v84
	v_exp_f32_e32 v85, v85
	v_exp_f32_e32 v86, v86
	v_mfma_f32_32x32x16_bf16 v[16:31], v[148:151], v[96:99], v[16:31]
	v_exp_f32_e32 v87, v87
	v_exp_f32_e32 v88, v88
	v_exp_f32_e32 v89, v89
	v_exp_f32_e32 v90, v90
	v_exp_f32_e32 v91, v91
	v_exp_f32_e32 v92, v92
	v_exp_f32_e32 v93, v93
	v_mfma_f32_32x32x16_bf16 v[0:15], v[144:147], v[100:103], v[0:15]
	v_exp_f32_e32 v94, v94
	v_exp_f32_e32 v95, v95
	v_mfma_f32_32x32x16_bf16 v[16:31], v[152:155], v[100:103], v[16:31]
	ds_read_b64_tr_b16 v[96:97], v156 offset:18432
	ds_read_b64_tr_b16 v[98:99], v156 offset:18944
	ds_read_b64_tr_b16 v[100:101], v156 offset:22528
	ds_read_b64_tr_b16 v[102:103], v156 offset:23040
	ds_read_b64_tr_b16 v[104:105], v156 offset:19456
	ds_read_b64_tr_b16 v[106:107], v156 offset:19968
	ds_read_b64_tr_b16 v[108:109], v156 offset:23552
	ds_read_b64_tr_b16 v[110:111], v156 offset:24064
	v_add_f32_e32 v124, v124, v80
	v_add_f32_e32 v125, v125, v81
	v_cvt_pk_bf16_f32 v80, v80, v81
	v_add_f32_e32 v124, v124, v82
	v_add_f32_e32 v125, v125, v83
	v_cvt_pk_bf16_f32 v81, v82, v83
	v_add_f32_e32 v124, v124, v84
	v_add_f32_e32 v125, v125, v85
	v_cvt_pk_bf16_f32 v82, v84, v85
	v_add_f32_e32 v124, v124, v86
	v_add_f32_e32 v125, v125, v87
	v_cvt_pk_bf16_f32 v83, v86, v87
	v_add_f32_e32 v124, v124, v88
	v_add_f32_e32 v125, v125, v89
	v_cvt_pk_bf16_f32 v84, v88, v89
	v_add_f32_e32 v124, v124, v90
	v_add_f32_e32 v125, v125, v91
	v_cvt_pk_bf16_f32 v85, v90, v91
	v_add_f32_e32 v124, v124, v92
	v_add_f32_e32 v125, v125, v93
	v_cvt_pk_bf16_f32 v86, v92, v93
	v_add_f32_e32 v124, v124, v94
	v_add_f32_e32 v125, v125, v95
	v_cvt_pk_bf16_f32 v87, v94, v95
	s_nop 0
	s_nop 0
	v_add_f32_e32 v88, v124, v125
	s_waitcnt lgkmcnt(0)
	v_mfma_f32_32x32x16_bf16 v[0:15], v[96:99], v[80:83], v[0:15]
	s_waitcnt vmcnt(2) lgkmcnt(0)
	s_barrier
	v_add_f32_e32 v139, v139, v88
	v_mfma_f32_32x32x16_bf16 v[16:31], v[100:103], v[80:83], v[16:31]
	v_mfma_f32_32x32x16_bf16 v[0:15], v[104:107], v[84:87], v[0:15]
	v_mfma_f32_32x32x16_bf16 v[16:31], v[108:111], v[84:87], v[16:31]
	v_mfma_f32_32x32x16_bf16 v[64:79], v[120:123], v[116:119], v[64:79]

.LBB0_748:
	s_mul_hi_u32 s5, s16, 0xaaaaaaab
	s_lshr_b32 s5, s5, 1
	s_add_i32 s4, s17, -4
	s_mul_i32 s5, s5, 0xffff7000
	s_waitcnt lgkmcnt(0)
	v_mfma_f32_32x32x16_bf16 v[96:111], v[84:87], v[112:115], v[32:47]
	v_add_u32_e32 v160, s5, v136
	v_exp_f32_e32 v48, v48
	v_exp_f32_e32 v49, v49
	v_exp_f32_e32 v50, v50
	v_exp_f32_e32 v51, v51
	v_exp_f32_e32 v52, v52
	v_exp_f32_e32 v53, v53
	v_exp_f32_e32 v54, v54
	v_exp_f32_e32 v55, v55
	v_mfma_f32_32x32x16_bf16 v[96:111], v[80:83], v[116:119], v[96:111]
	v_exp_f32_e32 v56, v56
	v_exp_f32_e32 v57, v57
	v_exp_f32_e32 v58, v58
	v_exp_f32_e32 v59, v59
	v_exp_f32_e32 v60, v60
	v_exp_f32_e32 v61, v61
	v_exp_f32_e32 v62, v62
	v_exp_f32_e32 v63, v63
	v_mfma_f32_32x32x16_bf16 v[80:95], v[124:127], v[112:115], v[32:47]
	ds_read_b64_tr_b16 v[140:141], v160 offset:4096
	ds_read_b64_tr_b16 v[142:143], v160 offset:4608
	ds_read_b64_tr_b16 v[144:145], v160 offset:5120
	ds_read_b64_tr_b16 v[146:147], v160 offset:5632
	ds_read_b64_tr_b16 v[148:149], v160 offset:8192
	ds_read_b64_tr_b16 v[150:151], v160 offset:8704
	ds_read_b64_tr_b16 v[152:153], v160 offset:9216
	ds_read_b64_tr_b16 v[154:155], v160 offset:9728
	v_add_f32_e32 v124, v215, v48
	v_add_f32_e32 v125, v215, v49
	v_cvt_pk_bf16_f32 v126, v52, v53
	v_add_f32_e32 v124, v124, v50
	v_add_f32_e32 v125, v125, v51
	v_cvt_pk_bf16_f32 v127, v54, v55
	v_add_f32_e32 v124, v124, v52
	v_add_f32_e32 v125, v125, v53
	v_cvt_pk_bf16_f32 v156, v56, v57
	v_add_f32_e32 v124, v124, v54
	v_add_f32_e32 v125, v125, v55
	v_cvt_pk_bf16_f32 v157, v58, v59
	v_add_f32_e32 v124, v124, v56
	v_add_f32_e32 v125, v125, v57
	v_cvt_pk_bf16_f32 v158, v60, v61
	v_add_f32_e32 v124, v124, v58
	v_add_f32_e32 v125, v125, v59
	v_cvt_pk_bf16_f32 v159, v62, v63
	v_add_f32_e32 v124, v124, v60
	v_add_f32_e32 v125, v125, v61
	v_add_f32_e32 v161, v124, v62
	v_add_f32_e32 v162, v125, v63
	v_cvt_pk_bf16_f32 v124, v48, v49
	v_cvt_pk_bf16_f32 v125, v50, v51
	s_waitcnt lgkmcnt(0)
	s_nop 0
	v_mfma_f32_32x32x16_bf16 v[0:15], v[140:143], v[124:127], v[0:15]
	v_exp_f32_e32 v64, v64
	v_exp_f32_e32 v65, v65
	v_exp_f32_e32 v66, v66
	v_exp_f32_e32 v67, v67
	v_exp_f32_e32 v68, v68
	v_exp_f32_e32 v69, v69
	v_exp_f32_e32 v70, v70
	v_mfma_f32_32x32x16_bf16 v[16:31], v[148:151], v[124:127], v[16:31]
	v_exp_f32_e32 v71, v71
	v_exp_f32_e32 v72, v72
	v_exp_f32_e32 v73, v73
	v_exp_f32_e32 v74, v74
	v_exp_f32_e32 v75, v75
	v_exp_f32_e32 v76, v76
	v_exp_f32_e32 v77, v77
	v_mfma_f32_32x32x16_bf16 v[0:15], v[144:147], v[156:159], v[0:15]
	ds_read_b64_tr_b16 v[124:125], v160 offset:6144
	ds_read_b64_tr_b16 v[126:127], v160 offset:6656
	ds_read_b64_tr_b16 v[140:141], v160 offset:10240
	ds_read_b64_tr_b16 v[142:143], v160 offset:10752
	ds_read_b64_tr_b16 v[144:145], v160 offset:7168
	ds_read_b64_tr_b16 v[146:147], v160 offset:7680
	ds_read_b64_tr_b16 v[148:149], v160 offset:11264
	ds_read_b64_tr_b16 v[150:151], v160 offset:11776
	v_exp_f32_e32 v78, v78
	v_exp_f32_e32 v79, v79
	s_nop 1
	v_mfma_f32_32x32x16_bf16 v[16:31], v[152:155], v[156:159], v[16:31]
	v_add_f32_e32 v152, v161, v64
	v_add_f32_e32 v153, v162, v65
	v_cvt_pk_bf16_f32 v154, v68, v69
	v_add_f32_e32 v152, v152, v66
	v_add_f32_e32 v153, v153, v67
	v_cvt_pk_bf16_f32 v155, v70, v71
	v_add_f32_e32 v152, v152, v68
	v_add_f32_e32 v153, v153, v69
	v_cvt_pk_bf16_f32 v156, v72, v73
	v_add_f32_e32 v152, v152, v70
	v_add_f32_e32 v153, v153, v71
	v_cvt_pk_bf16_f32 v157, v74, v75
	v_add_f32_e32 v152, v152, v72
	v_add_f32_e32 v153, v153, v73
	v_cvt_pk_bf16_f32 v158, v76, v77
	v_add_f32_e32 v152, v152, v74
	v_add_f32_e32 v153, v153, v75
	v_cvt_pk_bf16_f32 v159, v78, v79
	v_add_f32_e32 v152, v152, v76
	v_add_f32_e32 v153, v153, v77
	v_add_f32_e32 v160, v152, v78
	v_add_f32_e32 v161, v153, v79
	v_cvt_pk_bf16_f32 v152, v64, v65
	s_nop 0
	v_cvt_pk_bf16_f32 v153, v66, v67
	v_add_f32_e32 v160, v160, v161
	s_waitcnt lgkmcnt(0)
	v_mfma_f32_32x32x16_bf16 v[0:15], v[124:127], v[152:155], v[0:15]
	s_waitcnt vmcnt(2) lgkmcnt(0)
	s_barrier
	v_add_f32_e32 v139, v139, v160
	s_cmp_ge_u32 s4, s40
	v_mfma_f32_32x32x16_bf16 v[16:31], v[140:143], v[152:155], v[16:31]
	v_mfma_f32_32x32x16_bf16 v[0:15], v[144:147], v[156:159], v[0:15]
	v_mfma_f32_32x32x16_bf16 v[16:31], v[148:151], v[156:159], v[16:31]
	v_mfma_f32_32x32x16_bf16 v[80:95], v[120:123], v[116:119], v[80:95]
	s_cbranch_scc1 .LBB0_743
	s_min_u32 s4, s17, s40
	s_mul_hi_u32 s5, s4, 0x55555556
	s_mul_i32 s5, s5, 3
	s_sub_i32 s5, s4, s5
	s_mul_i32 s6, s5, 0x3000
	s_mul_i32 s4, s4, 0x50000
	s_mov_b32 s5, s81
	v_lshl_add_u64 v[48:49], v[128:129], 0, s[4:5]
	v_lshl_add_u64 v[48:49], v[48:49], 0, s[90:91]
	s_add_i32 m0, s93, s6
	s_add_i32 s4, s41, s95
	global_load_lds_dwordx4 v[48:49], off
	v_lshl_add_u64 v[48:49], v[130:131], 0, s[80:81]
	v_lshl_add_u64 v[48:49], v[48:49], 0, s[0:1]
	s_add_i32 m0, s4, 0x1000
	s_cmp_le_u32 s19, s39
	global_load_lds_dwordx4 v[48:49], off
	s_cbranch_scc1 .LBB0_751
	v_subrev_u32_e32 v48, 64, v137
	v_cmp_lt_i32_e64 s[4:5], -1, v48
	v_cmp_lt_i32_e64 s[6:7], 31, v48
	v_cmp_lt_i32_e32 vcc, 0, v48
	v_cndmask_b32_e64 v96, v249, v96, s[4:5]
	v_cmp_lt_i32_e64 s[4:5], 32, v48
	v_cndmask_b32_e64 v80, v249, v80, s[6:7]
	v_cmp_lt_i32_e64 s[6:7], 1, v48
	v_cndmask_b32_e32 v97, v249, v97, vcc
	v_cmp_lt_i32_e32 vcc, 33, v48
	v_cndmask_b32_e64 v81, v249, v81, s[4:5]
	v_cmp_lt_i32_e64 s[4:5], 2, v48
	v_cndmask_b32_e64 v98, v249, v98, s[6:7]
	v_cmp_lt_i32_e64 s[6:7], 34, v48
	v_cndmask_b32_e32 v82, v249, v82, vcc
	v_cmp_lt_i32_e32 vcc, 7, v48
	v_cndmask_b32_e64 v99, v249, v99, s[4:5]
	v_cmp_lt_i32_e64 s[4:5], 39, v48
	v_cndmask_b32_e64 v83, v249, v83, s[6:7]
	v_cmp_lt_i32_e64 s[6:7], 8, v48
	v_cndmask_b32_e32 v100, v249, v100, vcc
	v_cmp_lt_i32_e32 vcc, 40, v48
	v_cndmask_b32_e64 v84, v249, v84, s[4:5]
	v_cmp_lt_i32_e64 s[4:5], 9, v48
	v_cndmask_b32_e64 v101, v249, v101, s[6:7]
	v_cmp_lt_i32_e64 s[6:7], 41, v48
	v_cndmask_b32_e32 v85, v249, v85, vcc
	v_cmp_lt_i32_e32 vcc, 10, v48
	v_cndmask_b32_e64 v102, v249, v102, s[4:5]
	v_cmp_lt_i32_e64 s[4:5], 42, v48
	v_cndmask_b32_e64 v86, v249, v86, s[6:7]
	v_cmp_lt_i32_e64 s[6:7], 15, v48
	v_cndmask_b32_e32 v103, v249, v103, vcc
	v_cmp_lt_i32_e32 vcc, 47, v48
	v_cndmask_b32_e64 v87, v249, v87, s[4:5]
	v_cmp_lt_i32_e64 s[4:5], 16, v48
	v_cndmask_b32_e64 v104, v249, v104, s[6:7]
	v_cmp_lt_i32_e64 s[6:7], 48, v48
	v_cndmask_b32_e32 v88, v249, v88, vcc
	v_cmp_lt_i32_e32 vcc, 17, v48
	v_cndmask_b32_e64 v105, v249, v105, s[4:5]
	v_cmp_lt_i32_e64 s[4:5], 49, v48
	v_cndmask_b32_e64 v89, v249, v89, s[6:7]
	v_cmp_lt_i32_e64 s[6:7], 18, v48
	v_cndmask_b32_e32 v106, v249, v106, vcc
	v_cmp_lt_i32_e32 vcc, 50, v48
	v_cndmask_b32_e64 v90, v249, v90, s[4:5]
	v_cmp_lt_i32_e64 s[4:5], 23, v48
	v_cndmask_b32_e64 v107, v249, v107, s[6:7]
	v_cmp_lt_i32_e64 s[6:7], 55, v48
	v_cndmask_b32_e32 v91, v249, v91, vcc
	v_cmp_lt_i32_e32 vcc, 24, v48
	v_cndmask_b32_e64 v108, v249, v108, s[4:5]
	v_cmp_lt_i32_e64 s[4:5], 56, v48
	v_cndmask_b32_e64 v92, v249, v92, s[6:7]
	v_cmp_lt_i32_e64 s[6:7], 25, v48
	v_cndmask_b32_e32 v109, v249, v109, vcc
	v_cmp_lt_i32_e32 vcc, 57, v48
	v_cndmask_b32_e64 v93, v249, v93, s[4:5]
	v_cmp_lt_i32_e64 s[4:5], 26, v48
	v_cndmask_b32_e64 v110, v249, v110, s[6:7]
	v_cmp_lt_i32_e64 s[6:7], 58, v48
	v_cndmask_b32_e32 v94, v249, v94, vcc
	s_nop 0
	v_cndmask_b32_e64 v111, v249, v111, s[4:5]
	s_nop 0
	v_cndmask_b32_e64 v95, v249, v95, s[6:7]
